# code placement: every K-loop MFMA block start 8-byte aligned, on top of the best nt-hint version
# baseline (speedup 1.0000x reference)
; #define PG8_STAGE(bufoff, gbase, voff) do { _Pragma("unroll") for (int _i = 0; _i < 2; ++_i) \
;         __builtin_amdgcn_global_load_lds((const unsigned*)((const char*)(gbase) + (voff)[_i]), (PG8_LAS unsigned*)(lds + (bufoff) + ldsw + _i * 8192), 16, 0, 0); } while (0)
; #define PG8_LDA(dst, b, h) do { _Pragma("unroll") for (int m = 0; m < 4; ++m) _Pragma("unroll") for (int k = 0; k < 2; ++k) dst[m][k] = *(const PG8_LAS bf16x8*)(lds + PG8_SA(b, h) + aoff + m * 2048 + k * 1024); } while (0)
; #define PG8_LDB(dst, b, h) do { _Pragma("unroll") for (int n = 0; n < 2; ++n) _Pragma("unroll") for (int k = 0; k < 2; ++k) dst[n][k] = *(const PG8_LAS bf16x8*)(lds + PG8_SB(b, h) + boff + n * 2048 + k * 1024); } while (0)
; #define PG8_MMA(ai, bj, At, Bt) do { __builtin_amdgcn_s_setprio(1); _Pragma("unroll") for (int m = 0; m < 4; ++m) _Pragma("unroll") for (int n = 0; n < 2; ++n) _Pragma("unroll") for (int k = 0; k < 2; ++k) \
;         acc[ai][bj][m][n] = __builtin_amdgcn_mfma_f32_16x16x32_bf16(Bt[n][k], At[m][k], acc[ai][bj][m][n], 0, 0, 0); __builtin_amdgcn_s_setprio(0); } while (0)
; #define PG8_WAIT_V(n) asm volatile("s_waitcnt vmcnt(" #n ")" ::: "memory")
; #define PG8_WAIT_L(n) asm volatile("s_waitcnt lgkmcnt(" #n ")" ::: "memory")
; template <class Epi, class Sched, bool ALIGN_EPI = false, bool SP2 = false>
; __device__ __forceinline__ void gemm_phase(PG8_LAS unsigned char* lds, const Gemm g, const Sched& S, const Epi& E) {
;     ...
;             const bool last = (t == ntc - 2);
;             const char* a1 = cA + (size_t)(t + 1) * kstep;
;             const char* a2 = last ? nA : cA + (size_t)(t + 2) * kstep; const char* b2 = last ? nB : cB + (size_t)(t + 2) * kstep;
;             const char* a3 = a2 + kstep; const char* b3 = b2 + kstep;
;             if (last && has_next) S.a_ready(nxt);
;             if constexpr (SP2) {
;             PG8_LDB(B0, 0, 0); PG8_LDB(B1, 0, 1); PG8_SCHED; PG8_LDA(At, 0, 0); PG8_STAGE(PG8_SA(1, 1), a1 + hstep, voffA);
;             PG8_WAIT_V(8); PG8_WAIT_L(0); PG8_BAR; PG8_MMA(0, 0, At, B0); PG8_MMA(0, 1, At, B1); PG8_BAR; PG8_SCHED;
;             PG8_LDA(At, 0, 1); PG8_STAGE(PG8_SB(0, 0), b2, voffB); PG8_STAGE(PG8_SB(0, 1), b2 + hstep, voffB); PG8_STAGE(PG8_SA(0, 0), a2, voffA);
;             PG8_WAIT_V(8); PG8_WAIT_L(0); PG8_BAR; PG8_MMA(1, 0, At, B0); PG8_MMA(1, 1, At, B1); PG8_BAR; PG8_SCHED;
.LBB0_366:
	ds_read_b128 v[130:133], v228
	ds_read_b128 v[134:137], v228 offset:1024
	ds_read_b128 v[138:141], v228 offset:2048
	ds_read_b128 v[170:173], v228 offset:3072
	ds_read_b128 v[174:177], v229
	ds_read_b128 v[178:181], v229 offset:1024
	ds_read_b128 v[182:185], v229 offset:2048
	ds_read_b128 v[186:189], v229 offset:3072
	s_add_u32 s12, s10, 0xfff00080
	s_addc_u32 s13, s11, -1
	s_cmp_eq_u32 s80, 60
	s_cselect_b32 s15, s0, s13
	s_cselect_b32 s14, s1, s12
	s_cselect_b32 s13, s61, s77
	s_cselect_b32 s12, s69, s71
	s_add_i32 m0, s79, 0xc000
	ds_read_b128 v[190:193], v230
	ds_read_b128 v[194:197], v230 offset:1024
	ds_read_b128 v[198:201], v230 offset:2048
	ds_read_b128 v[202:205], v230 offset:3072
	ds_read_b128 v[206:209], v230 offset:4096
	ds_read_b128 v[210:213], v230 offset:5120
	ds_read_b128 v[214:217], v230 offset:6144
	ds_read_b128 v[218:221], v230 offset:7168
	global_load_lds_dwordx4 v164, s[10:11]
	s_add_i32 m0, s79, 0xe000
	s_nop 0
	global_load_lds_dwordx4 v166, s[10:11]
	s_waitcnt vmcnt(8)
	s_waitcnt lgkmcnt(0)
	s_barrier
	s_waitcnt lgkmcnt(0)
	v_mfma_f32_16x16x32_bf16 v[126:129], v[130:133], v[190:193], v[126:129]
	v_mfma_f32_16x16x32_bf16 v[126:129], v[134:137], v[194:197], v[126:129]
	v_mfma_f32_16x16x32_bf16 v[122:125], v[138:141], v[190:193], v[122:125]
	v_mfma_f32_16x16x32_bf16 v[122:125], v[170:173], v[194:197], v[122:125]
	v_mfma_f32_16x16x32_bf16 v[106:109], v[138:141], v[198:201], v[106:109]
	v_mfma_f32_16x16x32_bf16 v[106:109], v[170:173], v[202:205], v[106:109]
	v_mfma_f32_16x16x32_bf16 v[110:113], v[130:133], v[198:201], v[110:113]
	v_mfma_f32_16x16x32_bf16 v[110:113], v[134:137], v[202:205], v[110:113]
	v_mfma_f32_16x16x32_bf16 v[94:97], v[130:133], v[206:209], v[94:97]
	v_mfma_f32_16x16x32_bf16 v[94:97], v[134:137], v[210:213], v[94:97]
	v_mfma_f32_16x16x32_bf16 v[90:93], v[138:141], v[206:209], v[90:93]
	v_mfma_f32_16x16x32_bf16 v[90:93], v[170:173], v[210:213], v[90:93]
	v_mfma_f32_16x16x32_bf16 v[74:77], v[138:141], v[214:217], v[74:77]
	v_mfma_f32_16x16x32_bf16 v[74:77], v[170:173], v[218:221], v[74:77]
	v_mfma_f32_16x16x32_bf16 v[78:81], v[130:133], v[214:217], v[78:81]
	v_mfma_f32_16x16x32_bf16 v[78:81], v[134:137], v[218:221], v[78:81]
	v_mfma_f32_16x16x32_bf16 v[118:121], v[174:177], v[190:193], v[118:121]
	v_mfma_f32_16x16x32_bf16 v[118:121], v[178:181], v[194:197], v[118:121]
	v_mfma_f32_16x16x32_bf16 v[114:117], v[182:185], v[190:193], v[114:117]
	v_mfma_f32_16x16x32_bf16 v[114:117], v[186:189], v[194:197], v[114:117]
	v_mfma_f32_16x16x32_bf16 v[98:101], v[182:185], v[198:201], v[98:101]
	v_mfma_f32_16x16x32_bf16 v[98:101], v[186:189], v[202:205], v[98:101]
	v_mfma_f32_16x16x32_bf16 v[102:105], v[174:177], v[198:201], v[102:105]
	v_mfma_f32_16x16x32_bf16 v[102:105], v[178:181], v[202:205], v[102:105]
	v_mfma_f32_16x16x32_bf16 v[86:89], v[174:177], v[206:209], v[86:89]
	v_mfma_f32_16x16x32_bf16 v[86:89], v[178:181], v[210:213], v[86:89]
	v_mfma_f32_16x16x32_bf16 v[82:85], v[182:185], v[206:209], v[82:85]
	v_mfma_f32_16x16x32_bf16 v[82:85], v[186:189], v[210:213], v[82:85]
	v_mfma_f32_16x16x32_bf16 v[66:69], v[182:185], v[214:217], v[66:69]
	v_mfma_f32_16x16x32_bf16 v[66:69], v[186:189], v[218:221], v[66:69]
	v_mfma_f32_16x16x32_bf16 v[70:73], v[174:177], v[214:217], v[70:73]
	v_mfma_f32_16x16x32_bf16 v[70:73], v[178:181], v[218:221], v[70:73]
	s_barrier
	s_add_i32 s81, s63, s67
	s_mov_b32 m0, s81
	ds_read_b128 v[190:193], v230 offset:16384
	ds_read_b128 v[194:197], v230 offset:17408
	ds_read_b128 v[198:201], v230 offset:18432
	ds_read_b128 v[202:205], v230 offset:19456
	ds_read_b128 v[206:209], v230 offset:20480
	ds_read_b128 v[210:213], v230 offset:21504
	ds_read_b128 v[214:217], v230 offset:22528
	ds_read_b128 v[218:221], v230 offset:23552
	global_load_lds_dwordx4 v144, s[12:13]
	s_add_i32 m0, s81, 0x2000
	s_add_u32 s82, s12, 0x100000
	s_addc_u32 s83, s13, 0
	s_add_i32 s81, s94, s67
	global_load_lds_dwordx4 v148, s[12:13]
	s_mov_b32 m0, s81
	s_nop 0
	global_load_lds_dwordx4 v144, s[82:83]
	s_add_i32 m0, s81, 0x2000
	s_nop 0
	global_load_lds_dwordx4 v148, s[82:83]
	s_mov_b32 m0, s79
	s_nop 0
	global_load_lds_dwordx4 v142, s[14:15]
	s_mov_b32 m0, s88
	s_nop 0
	global_load_lds_dwordx4 v146, s[14:15]
	s_waitcnt vmcnt(8)
	s_waitcnt lgkmcnt(0)
	s_barrier
	s_waitcnt lgkmcnt(0)
	v_mfma_f32_16x16x32_bf16 v[62:65], v[130:133], v[190:193], v[62:65]
	v_mfma_f32_16x16x32_bf16 v[62:65], v[134:137], v[194:197], v[62:65]
	v_mfma_f32_16x16x32_bf16 v[58:61], v[138:141], v[190:193], v[58:61]
	v_mfma_f32_16x16x32_bf16 v[58:61], v[170:173], v[194:197], v[58:61]
	v_mfma_f32_16x16x32_bf16 v[42:45], v[138:141], v[198:201], v[42:45]
	v_mfma_f32_16x16x32_bf16 v[42:45], v[170:173], v[202:205], v[42:45]
	v_mfma_f32_16x16x32_bf16 v[46:49], v[130:133], v[198:201], v[46:49]
	v_mfma_f32_16x16x32_bf16 v[46:49], v[134:137], v[202:205], v[46:49]
	v_mfma_f32_16x16x32_bf16 v[30:33], v[130:133], v[206:209], v[30:33]
	v_mfma_f32_16x16x32_bf16 v[30:33], v[134:137], v[210:213], v[30:33]
	v_mfma_f32_16x16x32_bf16 v[26:29], v[138:141], v[206:209], v[26:29]
	v_mfma_f32_16x16x32_bf16 v[26:29], v[170:173], v[210:213], v[26:29]
	v_mfma_f32_16x16x32_bf16 v[10:13], v[138:141], v[214:217], v[10:13]
	v_mfma_f32_16x16x32_bf16 v[10:13], v[170:173], v[218:221], v[10:13]
	v_mfma_f32_16x16x32_bf16 v[14:17], v[130:133], v[214:217], v[14:17]
	v_mfma_f32_16x16x32_bf16 v[14:17], v[134:137], v[218:221], v[14:17]
	v_mfma_f32_16x16x32_bf16 v[54:57], v[174:177], v[190:193], v[54:57]
	v_mfma_f32_16x16x32_bf16 v[54:57], v[178:181], v[194:197], v[54:57]
	v_mfma_f32_16x16x32_bf16 v[50:53], v[182:185], v[190:193], v[50:53]
	v_mfma_f32_16x16x32_bf16 v[50:53], v[186:189], v[194:197], v[50:53]
	v_mfma_f32_16x16x32_bf16 v[34:37], v[182:185], v[198:201], v[34:37]
	v_mfma_f32_16x16x32_bf16 v[34:37], v[186:189], v[202:205], v[34:37]
	v_mfma_f32_16x16x32_bf16 v[38:41], v[174:177], v[198:201], v[38:41]
	v_mfma_f32_16x16x32_bf16 v[38:41], v[178:181], v[202:205], v[38:41]
	v_mfma_f32_16x16x32_bf16 v[22:25], v[174:177], v[206:209], v[22:25]
	v_mfma_f32_16x16x32_bf16 v[22:25], v[178:181], v[210:213], v[22:25]
	v_mfma_f32_16x16x32_bf16 v[18:21], v[182:185], v[206:209], v[18:21]
	v_mfma_f32_16x16x32_bf16 v[18:21], v[186:189], v[210:213], v[18:21]
	v_mfma_f32_16x16x32_bf16 v[2:5], v[182:185], v[214:217], v[2:5]
	v_mfma_f32_16x16x32_bf16 v[2:5], v[186:189], v[218:221], v[2:5]
	v_mfma_f32_16x16x32_bf16 v[6:9], v[174:177], v[214:217], v[6:9]
	v_mfma_f32_16x16x32_bf16 v[6:9], v[178:181], v[218:221], v[6:9]
	s_barrier
; #define PG8_STAGE(bufoff, gbase, voff) do { _Pragma("unroll") for (int _i = 0; _i < 2; ++_i) \
;         __builtin_amdgcn_global_load_lds((const unsigned*)((const char*)(gbase) + (voff)[_i]), (PG8_LAS unsigned*)(lds + (bufoff) + ldsw + _i * 8192), 16, 0, 0); } while (0)
; #define PG8_LDA(dst, b, h) do { _Pragma("unroll") for (int m = 0; m < 4; ++m) _Pragma("unroll") for (int k = 0; k < 2; ++k) dst[m][k] = *(const PG8_LAS bf16x8*)(lds + PG8_SA(b, h) + aoff + m * 2048 + k * 1024); } while (0)
; #define PG8_LDB(dst, b, h) do { _Pragma("unroll") for (int n = 0; n < 2; ++n) _Pragma("unroll") for (int k = 0; k < 2; ++k) dst[n][k] = *(const PG8_LAS bf16x8*)(lds + PG8_SB(b, h) + boff + n * 2048 + k * 1024); } while (0)
; #define PG8_MMA(ai, bj, At, Bt) do { __builtin_amdgcn_s_setprio(1); _Pragma("unroll") for (int m = 0; m < 4; ++m) _Pragma("unroll") for (int n = 0; n < 2; ++n) _Pragma("unroll") for (int k = 0; k < 2; ++k) \
;         acc[ai][bj][m][n] = __builtin_amdgcn_mfma_f32_16x16x32_bf16(Bt[n][k], At[m][k], acc[ai][bj][m][n], 0, 0, 0); __builtin_amdgcn_s_setprio(0); } while (0)
; #define PG8_WAIT_V(n) asm volatile("s_waitcnt vmcnt(" #n ")" ::: "memory")
; #define PG8_WAIT_L(n) asm volatile("s_waitcnt lgkmcnt(" #n ")" ::: "memory")
; #define PG8_BAR __builtin_amdgcn_s_barrier()
; #define PG8_SCHED __builtin_amdgcn_sched_barrier(0)
; template <class Epi, class Sched, bool ALIGN_EPI = false, bool SP2 = false>
; __device__ __forceinline__ void gemm_phase(PG8_LAS unsigned char* lds, const Gemm g, const Sched& S, const Epi& E) {
;     ...
;             PG8_LDB(B0, 1, 0); PG8_LDB(B1, 1, 1); PG8_SCHED; PG8_LDA(At, 1, 0); PG8_STAGE(PG8_SA(0, 1), a2 + hstep, voffA);
;             PG8_WAIT_V(8); PG8_WAIT_L(0); PG8_BAR; PG8_MMA(0, 0, At, B0); PG8_MMA(0, 1, At, B1); PG8_BAR; PG8_SCHED;
;             PG8_LDA(At, 1, 1); PG8_STAGE(PG8_SB(1, 0), b3, voffB); PG8_STAGE(PG8_SB(1, 1), b3 + hstep, voffB); PG8_STAGE(PG8_SA(1, 0), a3, voffA);
;             PG8_WAIT_V(8); PG8_WAIT_L(0); PG8_BAR; PG8_MMA(1, 0, At, B0); PG8_MMA(1, 1, At, B1); PG8_BAR; PG8_SCHED;
;     ...
;         if constexpr (ALIGN_EPI) { if (wr == 0) PG8_BAR; }
	s_add_i32 s81, 0, 0x18000
	v_add_u32_e32 v150, s81, v153
	s_add_i32 s82, 0, 0x1c000
	ds_read_b128 v[130:133], v150
	ds_read_b128 v[134:137], v150 offset:1024
	ds_read_b128 v[138:141], v150 offset:2048
	ds_read_b128 v[170:173], v150 offset:3072
	v_add_u32_e32 v150, s82, v153
	ds_read_b128 v[174:177], v150
	ds_read_b128 v[178:181], v150 offset:1024
	ds_read_b128 v[182:185], v150 offset:2048
	ds_read_b128 v[186:189], v150 offset:3072
	s_add_u32 s14, s14, 0x100000
	s_addc_u32 s15, s15, 0
	s_mov_b32 m0, s89
	ds_read_b128 v[190:193], v230 offset:32768
	ds_read_b128 v[194:197], v230 offset:33792
	ds_read_b128 v[198:201], v230 offset:34816
	ds_read_b128 v[202:205], v230 offset:35840
	ds_read_b128 v[206:209], v230 offset:36864
	ds_read_b128 v[210:213], v230 offset:37888
	ds_read_b128 v[214:217], v230 offset:38912
	ds_read_b128 v[218:221], v230 offset:39936
	global_load_lds_dwordx4 v142, s[14:15]
	s_mov_b32 m0, s90
	s_nop 0
	global_load_lds_dwordx4 v146, s[14:15]
	s_nop 0
	s_waitcnt vmcnt(8)
	s_waitcnt lgkmcnt(0)
	s_barrier
	s_waitcnt lgkmcnt(0)
	v_mfma_f32_16x16x32_bf16 v[126:129], v[130:133], v[190:193], v[126:129]
	v_mfma_f32_16x16x32_bf16 v[126:129], v[134:137], v[194:197], v[126:129]
	v_mfma_f32_16x16x32_bf16 v[122:125], v[138:141], v[190:193], v[122:125]
	v_mfma_f32_16x16x32_bf16 v[122:125], v[170:173], v[194:197], v[122:125]
	v_mfma_f32_16x16x32_bf16 v[106:109], v[138:141], v[198:201], v[106:109]
	v_mfma_f32_16x16x32_bf16 v[106:109], v[170:173], v[202:205], v[106:109]
	v_mfma_f32_16x16x32_bf16 v[110:113], v[130:133], v[198:201], v[110:113]
	v_mfma_f32_16x16x32_bf16 v[110:113], v[134:137], v[202:205], v[110:113]
	v_mfma_f32_16x16x32_bf16 v[94:97], v[130:133], v[206:209], v[94:97]
	v_mfma_f32_16x16x32_bf16 v[94:97], v[134:137], v[210:213], v[94:97]
	v_mfma_f32_16x16x32_bf16 v[90:93], v[138:141], v[206:209], v[90:93]
	v_mfma_f32_16x16x32_bf16 v[90:93], v[170:173], v[210:213], v[90:93]
	v_mfma_f32_16x16x32_bf16 v[74:77], v[138:141], v[214:217], v[74:77]
	v_mfma_f32_16x16x32_bf16 v[74:77], v[170:173], v[218:221], v[74:77]
	v_mfma_f32_16x16x32_bf16 v[78:81], v[130:133], v[214:217], v[78:81]
	v_mfma_f32_16x16x32_bf16 v[78:81], v[134:137], v[218:221], v[78:81]
	v_mfma_f32_16x16x32_bf16 v[118:121], v[174:177], v[190:193], v[118:121]
	v_mfma_f32_16x16x32_bf16 v[118:121], v[178:181], v[194:197], v[118:121]
	v_mfma_f32_16x16x32_bf16 v[114:117], v[182:185], v[190:193], v[114:117]
	v_mfma_f32_16x16x32_bf16 v[114:117], v[186:189], v[194:197], v[114:117]
	v_mfma_f32_16x16x32_bf16 v[98:101], v[182:185], v[198:201], v[98:101]
	v_mfma_f32_16x16x32_bf16 v[98:101], v[186:189], v[202:205], v[98:101]
	v_mfma_f32_16x16x32_bf16 v[102:105], v[174:177], v[198:201], v[102:105]
	v_mfma_f32_16x16x32_bf16 v[102:105], v[178:181], v[202:205], v[102:105]
	v_mfma_f32_16x16x32_bf16 v[86:89], v[174:177], v[206:209], v[86:89]
	v_mfma_f32_16x16x32_bf16 v[86:89], v[178:181], v[210:213], v[86:89]
	v_mfma_f32_16x16x32_bf16 v[82:85], v[182:185], v[206:209], v[82:85]
	v_mfma_f32_16x16x32_bf16 v[82:85], v[186:189], v[210:213], v[82:85]
	v_mfma_f32_16x16x32_bf16 v[66:69], v[182:185], v[214:217], v[66:69]
	v_mfma_f32_16x16x32_bf16 v[66:69], v[186:189], v[218:221], v[66:69]
	v_mfma_f32_16x16x32_bf16 v[70:73], v[174:177], v[214:217], v[70:73]
	v_mfma_f32_16x16x32_bf16 v[70:73], v[178:181], v[218:221], v[70:73]
	s_barrier
	s_add_u32 s100, s14, 0xfff00080
	s_addc_u32 s101, s15, -1
	s_add_u32 s98, s12, 0x80
	s_addc_u32 s99, s13, 0
	s_add_i32 s14, s81, s67
	s_mov_b32 m0, s14
	ds_read_b128 v[190:193], v230 offset:49152
	ds_read_b128 v[194:197], v230 offset:50176
	ds_read_b128 v[198:201], v230 offset:51200
	ds_read_b128 v[202:205], v230 offset:52224
	ds_read_b128 v[206:209], v230 offset:53248
	ds_read_b128 v[210:213], v230 offset:54272
	ds_read_b128 v[214:217], v230 offset:55296
	ds_read_b128 v[218:221], v230 offset:56320
	global_load_lds_dwordx4 v144, s[98:99]
	s_add_i32 m0, s14, 0x2000
	s_add_u32 s12, s12, 0x100080
	s_addc_u32 s13, s13, 0
	s_add_i32 s14, s82, s67
	global_load_lds_dwordx4 v148, s[98:99]
	s_mov_b32 m0, s14
	s_nop 0
	global_load_lds_dwordx4 v144, s[12:13]
	s_add_i32 m0, s14, 0x2000
	s_nop 0
	global_load_lds_dwordx4 v148, s[12:13]
	s_mov_b32 m0, s93
	s_nop 0
	global_load_lds_dwordx4 v142, s[100:101]
	s_mov_b32 m0, s62
	s_nop 0
	global_load_lds_dwordx4 v146, s[100:101]
	s_waitcnt vmcnt(8)
	s_waitcnt lgkmcnt(0)
	s_barrier
	s_waitcnt lgkmcnt(0)
	v_mfma_f32_16x16x32_bf16 v[62:65], v[130:133], v[190:193], v[62:65]
	v_mfma_f32_16x16x32_bf16 v[62:65], v[134:137], v[194:197], v[62:65]
	v_mfma_f32_16x16x32_bf16 v[58:61], v[138:141], v[190:193], v[58:61]
	v_mfma_f32_16x16x32_bf16 v[58:61], v[170:173], v[194:197], v[58:61]
	v_mfma_f32_16x16x32_bf16 v[42:45], v[138:141], v[198:201], v[42:45]
	v_mfma_f32_16x16x32_bf16 v[42:45], v[170:173], v[202:205], v[42:45]
	v_mfma_f32_16x16x32_bf16 v[46:49], v[130:133], v[198:201], v[46:49]
	v_mfma_f32_16x16x32_bf16 v[46:49], v[134:137], v[202:205], v[46:49]
	v_mfma_f32_16x16x32_bf16 v[30:33], v[130:133], v[206:209], v[30:33]
	v_mfma_f32_16x16x32_bf16 v[30:33], v[134:137], v[210:213], v[30:33]
	v_mfma_f32_16x16x32_bf16 v[26:29], v[138:141], v[206:209], v[26:29]
	v_mfma_f32_16x16x32_bf16 v[26:29], v[170:173], v[210:213], v[26:29]
	v_mfma_f32_16x16x32_bf16 v[10:13], v[138:141], v[214:217], v[10:13]
	v_mfma_f32_16x16x32_bf16 v[10:13], v[170:173], v[218:221], v[10:13]
	v_mfma_f32_16x16x32_bf16 v[14:17], v[130:133], v[214:217], v[14:17]
	v_mfma_f32_16x16x32_bf16 v[14:17], v[134:137], v[218:221], v[14:17]
	v_mfma_f32_16x16x32_bf16 v[54:57], v[174:177], v[190:193], v[54:57]
	v_mfma_f32_16x16x32_bf16 v[54:57], v[178:181], v[194:197], v[54:57]
	v_mfma_f32_16x16x32_bf16 v[50:53], v[182:185], v[190:193], v[50:53]
	v_mfma_f32_16x16x32_bf16 v[50:53], v[186:189], v[194:197], v[50:53]
	v_mfma_f32_16x16x32_bf16 v[34:37], v[182:185], v[198:201], v[34:37]
	v_mfma_f32_16x16x32_bf16 v[34:37], v[186:189], v[202:205], v[34:37]
	v_mfma_f32_16x16x32_bf16 v[38:41], v[174:177], v[198:201], v[38:41]
	v_mfma_f32_16x16x32_bf16 v[38:41], v[178:181], v[202:205], v[38:41]
	v_mfma_f32_16x16x32_bf16 v[22:25], v[174:177], v[206:209], v[22:25]
	v_mfma_f32_16x16x32_bf16 v[22:25], v[178:181], v[210:213], v[22:25]
	v_mfma_f32_16x16x32_bf16 v[18:21], v[182:185], v[206:209], v[18:21]
	v_mfma_f32_16x16x32_bf16 v[18:21], v[186:189], v[210:213], v[18:21]
	v_mfma_f32_16x16x32_bf16 v[2:5], v[182:185], v[214:217], v[2:5]
	v_mfma_f32_16x16x32_bf16 v[2:5], v[186:189], v[218:221], v[2:5]
	v_mfma_f32_16x16x32_bf16 v[6:9], v[174:177], v[214:217], v[6:9]
	v_mfma_f32_16x16x32_bf16 v[6:9], v[178:181], v[218:221], v[6:9]
	s_barrier
	s_add_i32 s80, s80, 2
	s_add_u32 s10, s10, 0x100
	s_addc_u32 s11, s11, 0
	s_add_u32 s71, s71, 0x100
	s_addc_u32 s77, s77, 0
	s_cmp_gt_u32 s80, 61
	s_cbranch_scc0 .LBB0_366
	s_and_b64 vcc, exec, s[28:29]
	s_cbranch_vccz .LBB0_369
	s_barrier

; #define PG8_STAGE(bufoff, gbase, voff) do { _Pragma("unroll") for (int _i = 0; _i < 2; ++_i) \
;         __builtin_amdgcn_global_load_lds((const unsigned*)((const char*)(gbase) + (voff)[_i]), (PG8_LAS unsigned*)(lds + (bufoff) + ldsw + _i * 8192), 16, 0, 0); } while (0)
; #define PG8_LDA(dst, b, h) do { _Pragma("unroll") for (int m = 0; m < 4; ++m) _Pragma("unroll") for (int k = 0; k < 2; ++k) dst[m][k] = *(const PG8_LAS bf16x8*)(lds + PG8_SA(b, h) + aoff + m * 2048 + k * 1024); } while (0)
; #define PG8_LDB(dst, b, h) do { _Pragma("unroll") for (int n = 0; n < 2; ++n) _Pragma("unroll") for (int k = 0; k < 2; ++k) dst[n][k] = *(const PG8_LAS bf16x8*)(lds + PG8_SB(b, h) + boff + n * 2048 + k * 1024); } while (0)
; #define PG8_MMA(ai, bj, At, Bt) do { __builtin_amdgcn_s_setprio(1); _Pragma("unroll") for (int m = 0; m < 4; ++m) _Pragma("unroll") for (int n = 0; n < 2; ++n) _Pragma("unroll") for (int k = 0; k < 2; ++k) \
;         acc[ai][bj][m][n] = __builtin_amdgcn_mfma_f32_16x16x32_bf16(Bt[n][k], At[m][k], acc[ai][bj][m][n], 0, 0, 0); __builtin_amdgcn_s_setprio(0); } while (0)
; #define PG8_WAIT_V(n) asm volatile("s_waitcnt vmcnt(" #n ")" ::: "memory")
; #define PG8_WAIT_L(n) asm volatile("s_waitcnt lgkmcnt(" #n ")" ::: "memory")
; template <class Epi, class Sched, bool ALIGN_EPI = false, bool SP2 = false>
; __device__ __forceinline__ void gemm_phase(PG8_LAS unsigned char* lds, const Gemm g, const Sched& S, const Epi& E) {
;     ...
;             const bool last = (t == ntc - 2);
;             const char* a1 = cA + (size_t)(t + 1) * kstep;
;             const char* a2 = last ? nA : cA + (size_t)(t + 2) * kstep; const char* b2 = last ? nB : cB + (size_t)(t + 2) * kstep;
;             const char* a3 = a2 + kstep; const char* b3 = b2 + kstep;
;             if (last && has_next) S.a_ready(nxt);
;             if constexpr (SP2) {
;             PG8_LDB(B0, 0, 0); PG8_LDB(B1, 0, 1); PG8_SCHED; PG8_LDA(At, 0, 0); PG8_STAGE(PG8_SA(1, 1), a1 + hstep, voffA);
;             PG8_WAIT_V(8); PG8_WAIT_L(0); PG8_BAR; PG8_MMA(0, 0, At, B0); PG8_MMA(0, 1, At, B1); PG8_BAR; PG8_SCHED;
;             PG8_LDA(At, 0, 1); PG8_STAGE(PG8_SB(0, 0), b2, voffB); PG8_STAGE(PG8_SB(0, 1), b2 + hstep, voffB); PG8_STAGE(PG8_SA(0, 0), a2, voffA);
;             PG8_WAIT_V(8); PG8_WAIT_L(0); PG8_BAR; PG8_MMA(1, 0, At, B0); PG8_MMA(1, 1, At, B1); PG8_BAR; PG8_SCHED;
.LBB0_2487:
	v_add_u32_e32 v3, s67, v183
	s_add_i32 s81, s50, 2
	ds_read_b128 v[154:157], v3
	ds_read_b128 v[158:161], v3 offset:1024
	ds_read_b128 v[162:165], v3 offset:2048
	ds_read_b128 v[166:169], v3 offset:3072
	v_add_u32_e32 v3, s68, v183
	s_add_u32 s51, s42, s46
	ds_read_b128 v[170:173], v3
	ds_read_b128 v[174:177], v3 offset:1024
	ds_read_b128 v[178:181], v3 offset:2048
	ds_read_b128 v[184:187], v3 offset:3072
	s_addc_u32 s52, s43, s47
	s_add_u32 s51, s51, 0x100
	s_addc_u32 s52, s52, 0
	s_add_u32 s82, s79, s46
	s_addc_u32 s83, s80, s47
	s_cmp_eq_u32 s9, s50
	s_cselect_b32 s53, s27, s52
	s_cselect_b32 s52, s35, s51
	s_cselect_b32 s51, s31, s83
	s_cselect_b32 s50, s78, s82
	v_lshl_add_u64 v[4:5], v[150:151], 0, s[46:47]
	s_add_i32 m0, s11, 0xc000
	ds_read_b128 v[188:191], v211
	ds_read_b128 v[192:195], v211 offset:1024
	ds_read_b128 v[196:199], v211 offset:2048
	ds_read_b128 v[200:203], v211 offset:3072
	ds_read_b128 v[204:207], v211 offset:4096
	ds_read_b128 v[212:215], v211 offset:5120
	ds_read_b128 v[216:219], v211 offset:6144
	ds_read_b128 v[220:223], v211 offset:7168
	global_load_lds_dwordx4 v[4:5], off
	v_lshl_add_u64 v[4:5], v[152:153], 0, s[46:47]
	s_add_i32 m0, s11, 0xe000
	s_nop 0
	global_load_lds_dwordx4 v[4:5], off
	s_waitcnt vmcnt(8)
	s_waitcnt lgkmcnt(0)
	s_barrier
	s_waitcnt lgkmcnt(0)
	v_mfma_f32_16x16x32_bf16 v[130:133], v[154:157], v[188:191], v[130:133]
	v_mfma_f32_16x16x32_bf16 v[130:133], v[158:161], v[192:195], v[130:133]
	v_mfma_f32_16x16x32_bf16 v[126:129], v[162:165], v[188:191], v[126:129]
	v_mfma_f32_16x16x32_bf16 v[126:129], v[166:169], v[192:195], v[126:129]
	v_mfma_f32_16x16x32_bf16 v[110:113], v[162:165], v[196:199], v[110:113]
	v_mfma_f32_16x16x32_bf16 v[110:113], v[166:169], v[200:203], v[110:113]
	v_mfma_f32_16x16x32_bf16 v[114:117], v[154:157], v[196:199], v[114:117]
	v_mfma_f32_16x16x32_bf16 v[114:117], v[158:161], v[200:203], v[114:117]
	v_mfma_f32_16x16x32_bf16 v[98:101], v[154:157], v[204:207], v[98:101]
	v_mfma_f32_16x16x32_bf16 v[98:101], v[158:161], v[212:215], v[98:101]
	v_mfma_f32_16x16x32_bf16 v[94:97], v[162:165], v[204:207], v[94:97]
	v_mfma_f32_16x16x32_bf16 v[94:97], v[166:169], v[212:215], v[94:97]
	v_mfma_f32_16x16x32_bf16 v[78:81], v[162:165], v[216:219], v[78:81]
	v_mfma_f32_16x16x32_bf16 v[78:81], v[166:169], v[220:223], v[78:81]
	v_mfma_f32_16x16x32_bf16 v[82:85], v[154:157], v[216:219], v[82:85]
	v_mfma_f32_16x16x32_bf16 v[82:85], v[158:161], v[220:223], v[82:85]
	v_mfma_f32_16x16x32_bf16 v[122:125], v[170:173], v[188:191], v[122:125]
	v_mfma_f32_16x16x32_bf16 v[122:125], v[174:177], v[192:195], v[122:125]
	v_mfma_f32_16x16x32_bf16 v[118:121], v[178:181], v[188:191], v[118:121]
	v_mfma_f32_16x16x32_bf16 v[118:121], v[184:187], v[192:195], v[118:121]
	v_mfma_f32_16x16x32_bf16 v[102:105], v[178:181], v[196:199], v[102:105]
	v_mfma_f32_16x16x32_bf16 v[102:105], v[184:187], v[200:203], v[102:105]
	v_mfma_f32_16x16x32_bf16 v[106:109], v[170:173], v[196:199], v[106:109]
	v_mfma_f32_16x16x32_bf16 v[106:109], v[174:177], v[200:203], v[106:109]
	v_mfma_f32_16x16x32_bf16 v[90:93], v[170:173], v[204:207], v[90:93]
	v_mfma_f32_16x16x32_bf16 v[90:93], v[174:177], v[212:215], v[90:93]
	v_mfma_f32_16x16x32_bf16 v[86:89], v[178:181], v[204:207], v[86:89]
	v_mfma_f32_16x16x32_bf16 v[86:89], v[184:187], v[212:215], v[86:89]
	v_mfma_f32_16x16x32_bf16 v[70:73], v[178:181], v[216:219], v[70:73]
	v_mfma_f32_16x16x32_bf16 v[70:73], v[184:187], v[220:223], v[70:73]
	v_mfma_f32_16x16x32_bf16 v[74:77], v[170:173], v[216:219], v[74:77]
	v_mfma_f32_16x16x32_bf16 v[74:77], v[174:177], v[220:223], v[74:77]
	s_barrier
	s_add_i32 s82, s67, s55
	s_mov_b32 m0, s82
	ds_read_b128 v[188:191], v211 offset:16384
	ds_read_b128 v[192:195], v211 offset:17408
	ds_read_b128 v[196:199], v211 offset:18432
	ds_read_b128 v[200:203], v211 offset:19456
	ds_read_b128 v[204:207], v211 offset:20480
	ds_read_b128 v[212:215], v211 offset:21504
	ds_read_b128 v[216:219], v211 offset:22528
	ds_read_b128 v[220:223], v211 offset:23552
	global_load_lds_dwordx4 v134, s[50:51]
	s_add_i32 m0, s82, 0x2000
	s_add_u32 s82, s50, 0x100000
	s_addc_u32 s83, s51, 0
	s_add_i32 s84, s68, s55
	global_load_lds_dwordx4 v136, s[50:51]
	s_mov_b32 m0, s84
	s_nop 0
	global_load_lds_dwordx4 v134, s[82:83]
	s_add_i32 m0, s84, 0x2000
	s_nop 0
	global_load_lds_dwordx4 v136, s[82:83]
	s_mov_b32 m0, s11
	s_nop 0
	global_load_lds_dwordx4 v134, s[52:53]
	s_mov_b32 m0, s57
	s_nop 0
	global_load_lds_dwordx4 v136, s[52:53]
	s_waitcnt vmcnt(8)
	s_waitcnt lgkmcnt(0)
	s_barrier
; #define PG8_STAGE(bufoff, gbase, voff) do { _Pragma("unroll") for (int _i = 0; _i < 2; ++_i) \
;         __builtin_amdgcn_global_load_lds((const unsigned*)((const char*)(gbase) + (voff)[_i]), (PG8_LAS unsigned*)(lds + (bufoff) + ldsw + _i * 8192), 16, 0, 0); } while (0)
; #define PG8_LDA(dst, b, h) do { _Pragma("unroll") for (int m = 0; m < 4; ++m) _Pragma("unroll") for (int k = 0; k < 2; ++k) dst[m][k] = *(const PG8_LAS bf16x8*)(lds + PG8_SA(b, h) + aoff + m * 2048 + k * 1024); } while (0)
; #define PG8_LDB(dst, b, h) do { _Pragma("unroll") for (int n = 0; n < 2; ++n) _Pragma("unroll") for (int k = 0; k < 2; ++k) dst[n][k] = *(const PG8_LAS bf16x8*)(lds + PG8_SB(b, h) + boff + n * 2048 + k * 1024); } while (0)
; #define PG8_MMA(ai, bj, At, Bt) do { __builtin_amdgcn_s_setprio(1); _Pragma("unroll") for (int m = 0; m < 4; ++m) _Pragma("unroll") for (int n = 0; n < 2; ++n) _Pragma("unroll") for (int k = 0; k < 2; ++k) \
;         acc[ai][bj][m][n] = __builtin_amdgcn_mfma_f32_16x16x32_bf16(Bt[n][k], At[m][k], acc[ai][bj][m][n], 0, 0, 0); __builtin_amdgcn_s_setprio(0); } while (0)
; #define PG8_WAIT_V(n) asm volatile("s_waitcnt vmcnt(" #n ")" ::: "memory")
; #define PG8_WAIT_L(n) asm volatile("s_waitcnt lgkmcnt(" #n ")" ::: "memory")
; #define PG8_BAR __builtin_amdgcn_s_barrier()
; #define PG8_SCHED __builtin_amdgcn_sched_barrier(0)
; template <class Epi, class Sched, bool ALIGN_EPI = false, bool SP2 = false>
; __device__ __forceinline__ void gemm_phase(PG8_LAS unsigned char* lds, const Gemm g, const Sched& S, const Epi& E) {
;     ...
;             PG8_WAIT_V(8); PG8_WAIT_L(0); PG8_BAR; PG8_MMA(0, 0, At, B0); PG8_MMA(0, 1, At, B1); PG8_BAR; PG8_SCHED;
;             PG8_LDA(At, 0, 1); PG8_STAGE(PG8_SB(0, 0), b2, voffB); PG8_STAGE(PG8_SB(0, 1), b2 + hstep, voffB); PG8_STAGE(PG8_SA(0, 0), a2, voffA);
;             PG8_WAIT_V(8); PG8_WAIT_L(0); PG8_BAR; PG8_MMA(1, 0, At, B0); PG8_MMA(1, 1, At, B1); PG8_BAR; PG8_SCHED;
;             PG8_LDB(B0, 1, 0); PG8_LDB(B1, 1, 1); PG8_SCHED; PG8_LDA(At, 1, 0); PG8_STAGE(PG8_SA(0, 1), a2 + hstep, voffA);
;             PG8_WAIT_V(8); PG8_WAIT_L(0); PG8_BAR; PG8_MMA(0, 0, At, B0); PG8_MMA(0, 1, At, B1); PG8_BAR; PG8_SCHED;
	s_waitcnt lgkmcnt(0)
	v_mfma_f32_16x16x32_bf16 v[66:69], v[154:157], v[188:191], v[66:69]
	v_mfma_f32_16x16x32_bf16 v[66:69], v[158:161], v[192:195], v[66:69]
	v_mfma_f32_16x16x32_bf16 v[62:65], v[162:165], v[188:191], v[62:65]
	v_mfma_f32_16x16x32_bf16 v[62:65], v[166:169], v[192:195], v[62:65]
	v_mfma_f32_16x16x32_bf16 v[46:49], v[162:165], v[196:199], v[46:49]
	v_mfma_f32_16x16x32_bf16 v[46:49], v[166:169], v[200:203], v[46:49]
	v_mfma_f32_16x16x32_bf16 v[50:53], v[154:157], v[196:199], v[50:53]
	v_mfma_f32_16x16x32_bf16 v[50:53], v[158:161], v[200:203], v[50:53]
	v_mfma_f32_16x16x32_bf16 v[34:37], v[154:157], v[204:207], v[34:37]
	v_mfma_f32_16x16x32_bf16 v[34:37], v[158:161], v[212:215], v[34:37]
	v_mfma_f32_16x16x32_bf16 v[30:33], v[162:165], v[204:207], v[30:33]
	v_mfma_f32_16x16x32_bf16 v[30:33], v[166:169], v[212:215], v[30:33]
	v_mfma_f32_16x16x32_bf16 v[14:17], v[162:165], v[216:219], v[14:17]
	v_mfma_f32_16x16x32_bf16 v[14:17], v[166:169], v[220:223], v[14:17]
	v_mfma_f32_16x16x32_bf16 v[18:21], v[154:157], v[216:219], v[18:21]
	v_mfma_f32_16x16x32_bf16 v[18:21], v[158:161], v[220:223], v[18:21]
	v_mfma_f32_16x16x32_bf16 v[58:61], v[170:173], v[188:191], v[58:61]
	v_mfma_f32_16x16x32_bf16 v[58:61], v[174:177], v[192:195], v[58:61]
	v_mfma_f32_16x16x32_bf16 v[54:57], v[178:181], v[188:191], v[54:57]
	v_mfma_f32_16x16x32_bf16 v[54:57], v[184:187], v[192:195], v[54:57]
	v_mfma_f32_16x16x32_bf16 v[42:45], v[170:173], v[196:199], v[42:45]
	v_mfma_f32_16x16x32_bf16 v[42:45], v[174:177], v[200:203], v[42:45]
	v_mfma_f32_16x16x32_bf16 v[38:41], v[178:181], v[196:199], v[38:41]
	v_mfma_f32_16x16x32_bf16 v[38:41], v[184:187], v[200:203], v[38:41]
	v_mfma_f32_16x16x32_bf16 v[26:29], v[170:173], v[204:207], v[26:29]
	v_mfma_f32_16x16x32_bf16 v[26:29], v[174:177], v[212:215], v[26:29]
	v_mfma_f32_16x16x32_bf16 v[22:25], v[178:181], v[204:207], v[22:25]
	v_mfma_f32_16x16x32_bf16 v[22:25], v[184:187], v[212:215], v[22:25]
	v_mfma_f32_16x16x32_bf16 v[10:13], v[170:173], v[216:219], v[10:13]
	v_mfma_f32_16x16x32_bf16 v[10:13], v[174:177], v[220:223], v[10:13]
	v_mfma_f32_16x16x32_bf16 v[4:7], v[178:181], v[216:219], v[6:9]
	v_mfma_f32_16x16x32_bf16 v[4:7], v[184:187], v[220:223], v[4:7]
	s_barrier
	s_add_i32 s82, 0, 0x18000
	v_add_u32_e32 v3, s82, v183
	s_add_i32 s83, 0, 0x1c000
	ds_read_b128 v[154:157], v3
	ds_read_b128 v[158:161], v3 offset:1024
	ds_read_b128 v[162:165], v3 offset:2048
	ds_read_b128 v[166:169], v3 offset:3072
	v_add_u32_e32 v3, s83, v183
	ds_read_b128 v[170:173], v3
	ds_read_b128 v[174:177], v3 offset:1024
	ds_read_b128 v[178:181], v3 offset:2048
	ds_read_b128 v[184:187], v3 offset:3072
	s_add_u32 s52, s52, 0x100000
	s_addc_u32 s53, s53, 0
	s_mov_b32 m0, s60
	ds_read_b128 v[188:191], v211 offset:32768
	ds_read_b128 v[192:195], v211 offset:33792
	ds_read_b128 v[196:199], v211 offset:34816
	ds_read_b128 v[200:203], v211 offset:35840
	ds_read_b128 v[204:207], v211 offset:36864
	ds_read_b128 v[212:215], v211 offset:37888
	ds_read_b128 v[216:219], v211 offset:38912
	ds_read_b128 v[220:223], v211 offset:39936
	global_load_lds_dwordx4 v134, s[52:53]
	s_mov_b32 m0, s61
	s_nop 0
	global_load_lds_dwordx4 v136, s[52:53]
	s_nop 0
	s_waitcnt vmcnt(8)
	s_waitcnt lgkmcnt(0)
	s_barrier
	s_waitcnt lgkmcnt(0)
	v_mfma_f32_16x16x32_bf16 v[130:133], v[154:157], v[188:191], v[130:133]
	v_mfma_f32_16x16x32_bf16 v[130:133], v[158:161], v[192:195], v[130:133]
	v_mfma_f32_16x16x32_bf16 v[126:129], v[162:165], v[188:191], v[126:129]
	v_mfma_f32_16x16x32_bf16 v[126:129], v[166:169], v[192:195], v[126:129]
	v_mfma_f32_16x16x32_bf16 v[110:113], v[162:165], v[196:199], v[110:113]
	v_mfma_f32_16x16x32_bf16 v[110:113], v[166:169], v[200:203], v[110:113]
	v_mfma_f32_16x16x32_bf16 v[114:117], v[154:157], v[196:199], v[114:117]
	v_mfma_f32_16x16x32_bf16 v[114:117], v[158:161], v[200:203], v[114:117]
	v_mfma_f32_16x16x32_bf16 v[98:101], v[154:157], v[204:207], v[98:101]
	v_mfma_f32_16x16x32_bf16 v[98:101], v[158:161], v[212:215], v[98:101]
	v_mfma_f32_16x16x32_bf16 v[94:97], v[162:165], v[204:207], v[94:97]
	v_mfma_f32_16x16x32_bf16 v[94:97], v[166:169], v[212:215], v[94:97]
	v_mfma_f32_16x16x32_bf16 v[78:81], v[162:165], v[216:219], v[78:81]
	v_mfma_f32_16x16x32_bf16 v[78:81], v[166:169], v[220:223], v[78:81]
	v_mfma_f32_16x16x32_bf16 v[82:85], v[154:157], v[216:219], v[82:85]
	v_mfma_f32_16x16x32_bf16 v[82:85], v[158:161], v[220:223], v[82:85]
	v_mfma_f32_16x16x32_bf16 v[122:125], v[170:173], v[188:191], v[122:125]
	v_mfma_f32_16x16x32_bf16 v[122:125], v[174:177], v[192:195], v[122:125]
	v_mfma_f32_16x16x32_bf16 v[118:121], v[178:181], v[188:191], v[118:121]
	v_mfma_f32_16x16x32_bf16 v[118:121], v[184:187], v[192:195], v[118:121]
	v_mfma_f32_16x16x32_bf16 v[102:105], v[178:181], v[196:199], v[102:105]
	v_mfma_f32_16x16x32_bf16 v[102:105], v[184:187], v[200:203], v[102:105]
	v_mfma_f32_16x16x32_bf16 v[106:109], v[170:173], v[196:199], v[106:109]
	v_mfma_f32_16x16x32_bf16 v[106:109], v[174:177], v[200:203], v[106:109]
	v_mfma_f32_16x16x32_bf16 v[90:93], v[170:173], v[204:207], v[90:93]
	v_mfma_f32_16x16x32_bf16 v[90:93], v[174:177], v[212:215], v[90:93]
	v_mfma_f32_16x16x32_bf16 v[86:89], v[178:181], v[204:207], v[86:89]
	v_mfma_f32_16x16x32_bf16 v[86:89], v[184:187], v[212:215], v[86:89]
	v_mfma_f32_16x16x32_bf16 v[70:73], v[178:181], v[216:219], v[70:73]
	v_mfma_f32_16x16x32_bf16 v[70:73], v[184:187], v[220:223], v[70:73]
	v_mfma_f32_16x16x32_bf16 v[74:77], v[170:173], v[216:219], v[74:77]
	v_mfma_f32_16x16x32_bf16 v[74:77], v[174:177], v[220:223], v[74:77]
	s_barrier
; #define PG8_STAGE(bufoff, gbase, voff) do { _Pragma("unroll") for (int _i = 0; _i < 2; ++_i) \
;         __builtin_amdgcn_global_load_lds((const unsigned*)((const char*)(gbase) + (voff)[_i]), (PG8_LAS unsigned*)(lds + (bufoff) + ldsw + _i * 8192), 16, 0, 0); } while (0)
; #define PG8_LDA(dst, b, h) do { _Pragma("unroll") for (int m = 0; m < 4; ++m) _Pragma("unroll") for (int k = 0; k < 2; ++k) dst[m][k] = *(const PG8_LAS bf16x8*)(lds + PG8_SA(b, h) + aoff + m * 2048 + k * 1024); } while (0)
; #define PG8_MMA(ai, bj, At, Bt) do { __builtin_amdgcn_s_setprio(1); _Pragma("unroll") for (int m = 0; m < 4; ++m) _Pragma("unroll") for (int n = 0; n < 2; ++n) _Pragma("unroll") for (int k = 0; k < 2; ++k) \
;         acc[ai][bj][m][n] = __builtin_amdgcn_mfma_f32_16x16x32_bf16(Bt[n][k], At[m][k], acc[ai][bj][m][n], 0, 0, 0); __builtin_amdgcn_s_setprio(0); } while (0)
; #define PG8_WAIT_V(n) asm volatile("s_waitcnt vmcnt(" #n ")" ::: "memory")
; #define PG8_WAIT_L(n) asm volatile("s_waitcnt lgkmcnt(" #n ")" ::: "memory")
; #define PG8_BAR __builtin_amdgcn_s_barrier()
; #define PG8_SCHED __builtin_amdgcn_sched_barrier(0)
; template <class Epi, class Sched, bool ALIGN_EPI = false, bool SP2 = false>
; __device__ __forceinline__ void gemm_phase(PG8_LAS unsigned char* lds, const Gemm g, const Sched& S, const Epi& E) {
;     ...
;         for (int t = 0; t < ntc; t += 2) {
;     ...
;             PG8_LDA(At, 1, 1); PG8_STAGE(PG8_SB(1, 0), b3, voffB); PG8_STAGE(PG8_SB(1, 1), b3 + hstep, voffB); PG8_STAGE(PG8_SA(1, 0), a3, voffA);
;             PG8_WAIT_V(8); PG8_WAIT_L(0); PG8_BAR; PG8_MMA(1, 0, At, B0); PG8_MMA(1, 1, At, B1); PG8_BAR; PG8_SCHED;
	s_add_u32 s100, s52, 0xfff00080
	s_addc_u32 s101, s53, -1
	s_add_u32 s98, s50, 0x80
	s_addc_u32 s99, s51, 0
	s_add_i32 s52, s82, s55
	s_mov_b32 m0, s52
	ds_read_b128 v[188:191], v211 offset:49152
	ds_read_b128 v[192:195], v211 offset:50176
	ds_read_b128 v[196:199], v211 offset:51200
	ds_read_b128 v[200:203], v211 offset:52224
	ds_read_b128 v[204:207], v211 offset:53248
	ds_read_b128 v[212:215], v211 offset:54272
	ds_read_b128 v[216:219], v211 offset:55296
	ds_read_b128 v[220:223], v211 offset:56320
	global_load_lds_dwordx4 v134, s[98:99]
	s_add_i32 m0, s52, 0x2000
	s_add_u32 s50, s50, 0x100080
	s_addc_u32 s51, s51, 0
	s_add_i32 s52, s83, s55
	global_load_lds_dwordx4 v136, s[98:99]
	s_mov_b32 m0, s52
	s_nop 0
	global_load_lds_dwordx4 v134, s[50:51]
	s_add_i32 m0, s52, 0x2000
	s_nop 0
	global_load_lds_dwordx4 v136, s[50:51]
	s_mov_b32 m0, s63
	s_nop 0
	global_load_lds_dwordx4 v134, s[100:101]
	s_mov_b32 m0, s64
	s_nop 0
	global_load_lds_dwordx4 v136, s[100:101]
	s_waitcnt vmcnt(8)
	s_waitcnt lgkmcnt(0)
	s_barrier
	s_waitcnt lgkmcnt(0)
	v_mfma_f32_16x16x32_bf16 v[66:69], v[154:157], v[188:191], v[66:69]
	v_mfma_f32_16x16x32_bf16 v[66:69], v[158:161], v[192:195], v[66:69]
	v_mfma_f32_16x16x32_bf16 v[62:65], v[162:165], v[188:191], v[62:65]
	v_mfma_f32_16x16x32_bf16 v[62:65], v[166:169], v[192:195], v[62:65]
	v_mfma_f32_16x16x32_bf16 v[46:49], v[162:165], v[196:199], v[46:49]
	v_mfma_f32_16x16x32_bf16 v[46:49], v[166:169], v[200:203], v[46:49]
	v_mfma_f32_16x16x32_bf16 v[50:53], v[154:157], v[196:199], v[50:53]
	v_mfma_f32_16x16x32_bf16 v[50:53], v[158:161], v[200:203], v[50:53]
	v_mfma_f32_16x16x32_bf16 v[34:37], v[154:157], v[204:207], v[34:37]
	v_mfma_f32_16x16x32_bf16 v[34:37], v[158:161], v[212:215], v[34:37]
	v_mfma_f32_16x16x32_bf16 v[30:33], v[162:165], v[204:207], v[30:33]
	v_mfma_f32_16x16x32_bf16 v[30:33], v[166:169], v[212:215], v[30:33]
	v_mfma_f32_16x16x32_bf16 v[14:17], v[162:165], v[216:219], v[14:17]
	v_mfma_f32_16x16x32_bf16 v[14:17], v[166:169], v[220:223], v[14:17]
	v_mfma_f32_16x16x32_bf16 v[18:21], v[154:157], v[216:219], v[18:21]
	v_mfma_f32_16x16x32_bf16 v[18:21], v[158:161], v[220:223], v[18:21]
	v_mfma_f32_16x16x32_bf16 v[58:61], v[170:173], v[188:191], v[58:61]
	v_mfma_f32_16x16x32_bf16 v[58:61], v[174:177], v[192:195], v[58:61]
	v_mfma_f32_16x16x32_bf16 v[54:57], v[178:181], v[188:191], v[54:57]
	v_mfma_f32_16x16x32_bf16 v[54:57], v[184:187], v[192:195], v[54:57]
	v_mfma_f32_16x16x32_bf16 v[42:45], v[170:173], v[196:199], v[42:45]
	v_mfma_f32_16x16x32_bf16 v[42:45], v[174:177], v[200:203], v[42:45]
	v_mfma_f32_16x16x32_bf16 v[38:41], v[178:181], v[196:199], v[38:41]
	v_mfma_f32_16x16x32_bf16 v[38:41], v[184:187], v[200:203], v[38:41]
	v_mfma_f32_16x16x32_bf16 v[26:29], v[170:173], v[204:207], v[26:29]
	v_mfma_f32_16x16x32_bf16 v[26:29], v[174:177], v[212:215], v[26:29]
	v_mfma_f32_16x16x32_bf16 v[22:25], v[178:181], v[204:207], v[22:25]
	v_mfma_f32_16x16x32_bf16 v[22:25], v[184:187], v[212:215], v[22:25]
	v_mfma_f32_16x16x32_bf16 v[8:11], v[170:173], v[216:219], v[10:13]
	v_mfma_f32_16x16x32_bf16 v[10:13], v[174:177], v[220:223], v[8:11]
	v_mfma_f32_16x16x32_bf16 v[4:7], v[178:181], v[216:219], v[4:7]
	v_mfma_f32_16x16x32_bf16 v[6:9], v[184:187], v[220:223], v[4:7]
	s_barrier
	s_add_u32 s46, s46, 0x100
	s_addc_u32 s47, s47, 0
	s_cmp_ge_i32 s81, s77
	s_cbranch_scc1 .LBB0_2489
	s_mov_b32 s50, s81
	s_branch .LBB0_2485

; #define PG8_STAGE(bufoff, gbase, voff) do { _Pragma("unroll") for (int _i = 0; _i < 2; ++_i) \
;         __builtin_amdgcn_global_load_lds((const unsigned*)((const char*)(gbase) + (voff)[_i]), (PG8_LAS unsigned*)(lds + (bufoff) + ldsw + _i * 8192), 16, 0, 0); } while (0)
; #define PG8_LDA(dst, b, h) do { _Pragma("unroll") for (int m = 0; m < 4; ++m) _Pragma("unroll") for (int k = 0; k < 2; ++k) dst[m][k] = *(const PG8_LAS bf16x8*)(lds + PG8_SA(b, h) + aoff + m * 2048 + k * 1024); } while (0)
; #define PG8_LDB(dst, b, h) do { _Pragma("unroll") for (int n = 0; n < 2; ++n) _Pragma("unroll") for (int k = 0; k < 2; ++k) dst[n][k] = *(const PG8_LAS bf16x8*)(lds + PG8_SB(b, h) + boff + n * 2048 + k * 1024); } while (0)
; #define PG8_MMA(ai, bj, At, Bt) do { __builtin_amdgcn_s_setprio(1); _Pragma("unroll") for (int m = 0; m < 4; ++m) _Pragma("unroll") for (int n = 0; n < 2; ++n) _Pragma("unroll") for (int k = 0; k < 2; ++k) \
;         acc[ai][bj][m][n] = __builtin_amdgcn_mfma_f32_16x16x32_bf16(Bt[n][k], At[m][k], acc[ai][bj][m][n], 0, 0, 0); __builtin_amdgcn_s_setprio(0); } while (0)
; #define PG8_WAIT_V(n) asm volatile("s_waitcnt vmcnt(" #n ")" ::: "memory")
; #define PG8_WAIT_L(n) asm volatile("s_waitcnt lgkmcnt(" #n ")" ::: "memory")
; template <class Epi, class Sched, bool ALIGN_EPI = false, bool SP2 = false>
; __device__ __forceinline__ void gemm_phase(PG8_LAS unsigned char* lds, const Gemm g, const Sched& S, const Epi& E) {
;     ...
;             const bool last = (t == ntc - 2);
;             const char* a1 = cA + (size_t)(t + 1) * kstep;
;             const char* a2 = last ? nA : cA + (size_t)(t + 2) * kstep; const char* b2 = last ? nB : cB + (size_t)(t + 2) * kstep;
;             const char* a3 = a2 + kstep; const char* b3 = b2 + kstep;
;             if (last && has_next) S.a_ready(nxt);
;             if constexpr (SP2) {
;             PG8_LDB(B0, 0, 0); PG8_LDB(B1, 0, 1); PG8_SCHED; PG8_LDA(At, 0, 0); PG8_STAGE(PG8_SA(1, 1), a1 + hstep, voffA);
;             PG8_WAIT_V(8); PG8_WAIT_L(0); PG8_BAR; PG8_MMA(0, 0, At, B0); PG8_MMA(0, 1, At, B1); PG8_BAR; PG8_SCHED;
;             PG8_LDA(At, 0, 1); PG8_STAGE(PG8_SB(0, 0), b2, voffB); PG8_STAGE(PG8_SB(0, 1), b2 + hstep, voffB); PG8_STAGE(PG8_SA(0, 0), a2, voffA);
;             PG8_WAIT_V(8); PG8_WAIT_L(0); PG8_BAR; PG8_MMA(1, 0, At, B0); PG8_MMA(1, 1, At, B1); PG8_BAR; PG8_SCHED;
.LBB0_2650:
	ds_read_b128 v[10:13], v195
	ds_read_b128 v[14:17], v195 offset:1024
	ds_read_b128 v[42:45], v195 offset:2048
	ds_read_b128 v[46:49], v195 offset:3072
	ds_read_b128 v[50:53], v238
	ds_read_b128 v[54:57], v238 offset:1024
	ds_read_b128 v[58:61], v238 offset:2048
	ds_read_b128 v[62:65], v238 offset:3072
	s_add_u32 s88, s86, 0xfff00080
	s_addc_u32 s89, s87, -1
	s_cmp_eq_u32 s93, 60
	s_cselect_b32 s91, s19, s89
	s_cselect_b32 s90, s69, s88
	s_cselect_b32 s89, s77, s92
	s_cselect_b32 s88, s79, s85
	s_add_i32 m0, s62, 0xc000
	ds_read_b128 v[66:69], v239
	ds_read_b128 v[70:73], v239 offset:1024
	ds_read_b128 v[170:173], v239 offset:2048
	ds_read_b128 v[174:177], v239 offset:3072
	ds_read_b128 v[178:181], v239 offset:4096
	ds_read_b128 v[208:211], v239 offset:5120
	ds_read_b128 v[212:215], v239 offset:6144
	ds_read_b128 v[216:219], v239 offset:7168
	global_load_lds_dwordx4 v200, s[86:87]
	s_add_i32 m0, s62, 0xe000
	s_nop 0
	global_load_lds_dwordx4 v202, s[86:87]
	s_nop 0
	s_waitcnt vmcnt(8)
	s_waitcnt lgkmcnt(0)
	s_barrier
	s_waitcnt lgkmcnt(0)
	v_mfma_f32_16x16x32_bf16 v[6:9], v[10:13], v[66:69], v[6:9]
	v_mfma_f32_16x16x32_bf16 v[6:9], v[14:17], v[70:73], v[6:9]
	v_mfma_f32_16x16x32_bf16 v[2:5], v[42:45], v[66:69], v[2:5]
	v_mfma_f32_16x16x32_bf16 v[2:5], v[46:49], v[70:73], v[2:5]
	v_mfma_f32_16x16x32_bf16 v[154:157], v[42:45], v[170:173], v[154:157]
	v_mfma_f32_16x16x32_bf16 v[154:157], v[46:49], v[174:177], v[154:157]
	v_mfma_f32_16x16x32_bf16 v[158:161], v[10:13], v[170:173], v[158:161]
	v_mfma_f32_16x16x32_bf16 v[158:161], v[14:17], v[174:177], v[158:161]
	v_mfma_f32_16x16x32_bf16 v[142:145], v[10:13], v[178:181], v[142:145]
	v_mfma_f32_16x16x32_bf16 v[142:145], v[14:17], v[208:211], v[142:145]
	v_mfma_f32_16x16x32_bf16 v[138:141], v[42:45], v[178:181], v[138:141]
	v_mfma_f32_16x16x32_bf16 v[138:141], v[46:49], v[208:211], v[138:141]
	v_mfma_f32_16x16x32_bf16 v[122:125], v[42:45], v[212:215], v[122:125]
	v_mfma_f32_16x16x32_bf16 v[122:125], v[46:49], v[216:219], v[122:125]
	v_mfma_f32_16x16x32_bf16 v[126:129], v[10:13], v[212:215], v[126:129]
	v_mfma_f32_16x16x32_bf16 v[126:129], v[14:17], v[216:219], v[126:129]
	v_mfma_f32_16x16x32_bf16 v[166:169], v[50:53], v[66:69], v[166:169]
	v_mfma_f32_16x16x32_bf16 v[166:169], v[54:57], v[70:73], v[166:169]
	v_mfma_f32_16x16x32_bf16 v[66:69], v[58:61], v[66:69], v[162:165]
	v_mfma_f32_16x16x32_bf16 v[66:69], v[62:65], v[70:73], v[66:69]
	v_mfma_f32_16x16x32_bf16 v[146:149], v[58:61], v[170:173], v[146:149]
	v_mfma_f32_16x16x32_bf16 v[146:149], v[62:65], v[174:177], v[146:149]
	v_mfma_f32_16x16x32_bf16 v[134:137], v[50:53], v[178:181], v[134:137]
	v_mfma_f32_16x16x32_bf16 v[134:137], v[54:57], v[208:211], v[134:137]
	v_mfma_f32_16x16x32_bf16 v[130:133], v[58:61], v[178:181], v[130:133]
	v_mfma_f32_16x16x32_bf16 v[130:133], v[62:65], v[208:211], v[130:133]
	v_mfma_f32_16x16x32_bf16 v[118:121], v[50:53], v[212:215], v[118:121]
	v_mfma_f32_16x16x32_bf16 v[118:121], v[54:57], v[216:219], v[118:121]
	v_mfma_f32_16x16x32_bf16 v[114:117], v[58:61], v[212:215], v[114:117]
	v_mfma_f32_16x16x32_bf16 v[114:117], v[62:65], v[216:219], v[114:117]
	v_mfma_f32_16x16x32_bf16 v[70:73], v[50:53], v[170:173], v[150:153]
	v_mfma_f32_16x16x32_bf16 v[70:73], v[54:57], v[174:177], v[70:73]
	s_barrier
	s_add_i32 vcc_lo, s96, s61
	s_mov_b32 m0, vcc_lo
	ds_read_b128 v[150:153], v239 offset:16384
	ds_read_b128 v[162:165], v239 offset:17408
	ds_read_b128 v[170:173], v239 offset:18432
	ds_read_b128 v[174:177], v239 offset:19456
	ds_read_b128 v[178:181], v239 offset:20480
	ds_read_b128 v[208:211], v239 offset:21504
	ds_read_b128 v[212:215], v239 offset:22528
	ds_read_b128 v[216:219], v239 offset:23552
	global_load_lds_dwordx4 v186, s[88:89]
	s_add_i32 m0, vcc_lo, 0x2000
	s_add_u32 vcc_lo, s88, 0x100000
	s_addc_u32 vcc_hi, s89, 0
	s_add_i32 s58, s70, s61
	global_load_lds_dwordx4 v190, s[88:89]
	s_mov_b32 m0, s58
	s_nop 0
	global_load_lds_dwordx4 v186, vcc
	s_add_i32 m0, s58, 0x2000
	s_nop 0
	global_load_lds_dwordx4 v190, vcc
	s_mov_b32 m0, s62
	s_nop 0
	global_load_lds_dwordx4 v184, s[90:91]
	s_mov_b32 m0, s63
	s_nop 0
	global_load_lds_dwordx4 v188, s[90:91]
	s_waitcnt vmcnt(8)
	s_waitcnt lgkmcnt(0)
	s_barrier
	s_waitcnt lgkmcnt(0)
	v_mfma_f32_16x16x32_bf16 v[110:113], v[10:13], v[150:153], v[110:113]
	v_mfma_f32_16x16x32_bf16 v[110:113], v[14:17], v[162:165], v[110:113]
	v_mfma_f32_16x16x32_bf16 v[106:109], v[42:45], v[150:153], v[106:109]
	v_mfma_f32_16x16x32_bf16 v[106:109], v[46:49], v[162:165], v[106:109]
	v_mfma_f32_16x16x32_bf16 v[94:97], v[10:13], v[170:173], v[94:97]
	v_mfma_f32_16x16x32_bf16 v[94:97], v[14:17], v[174:177], v[94:97]
	v_mfma_f32_16x16x32_bf16 v[90:93], v[42:45], v[170:173], v[90:93]
	v_mfma_f32_16x16x32_bf16 v[90:93], v[46:49], v[174:177], v[90:93]
	v_mfma_f32_16x16x32_bf16 v[78:81], v[10:13], v[178:181], v[78:81]
	v_mfma_f32_16x16x32_bf16 v[78:81], v[14:17], v[208:211], v[78:81]
	v_mfma_f32_16x16x32_bf16 v[74:77], v[42:45], v[178:181], v[74:77]
	v_mfma_f32_16x16x32_bf16 v[74:77], v[46:49], v[208:211], v[74:77]
	v_mfma_f32_16x16x32_bf16 v[10:13], v[10:13], v[212:215], v[30:33]
	v_mfma_f32_16x16x32_bf16 v[10:13], v[14:17], v[216:219], v[10:13]
	v_mfma_f32_16x16x32_bf16 v[14:17], v[42:45], v[212:215], v[26:29]
	v_mfma_f32_16x16x32_bf16 v[14:17], v[46:49], v[216:219], v[14:17]
	v_mfma_f32_16x16x32_bf16 v[26:29], v[50:53], v[150:153], v[102:105]
	v_mfma_f32_16x16x32_bf16 v[42:45], v[54:57], v[162:165], v[26:29]
	v_mfma_f32_16x16x32_bf16 v[26:29], v[58:61], v[150:153], v[98:101]
	v_mfma_f32_16x16x32_bf16 v[46:49], v[62:65], v[162:165], v[26:29]
	v_mfma_f32_16x16x32_bf16 v[26:29], v[50:53], v[170:173], v[86:89]
	v_mfma_f32_16x16x32_bf16 v[86:89], v[54:57], v[174:177], v[26:29]
	v_mfma_f32_16x16x32_bf16 v[26:29], v[58:61], v[170:173], v[82:85]
	v_mfma_f32_16x16x32_bf16 v[82:85], v[62:65], v[174:177], v[26:29]
	v_mfma_f32_16x16x32_bf16 v[26:29], v[50:53], v[178:181], v[38:41]
	v_mfma_f32_16x16x32_bf16 v[38:41], v[54:57], v[208:211], v[26:29]
	v_mfma_f32_16x16x32_bf16 v[26:29], v[58:61], v[178:181], v[34:37]
	v_mfma_f32_16x16x32_bf16 v[34:37], v[62:65], v[208:211], v[26:29]
	v_mfma_f32_16x16x32_bf16 v[22:25], v[50:53], v[212:215], v[22:25]
	v_mfma_f32_16x16x32_bf16 v[22:25], v[54:57], v[216:219], v[22:25]
	v_mfma_f32_16x16x32_bf16 v[18:21], v[58:61], v[212:215], v[18:21]
	v_mfma_f32_16x16x32_bf16 v[18:21], v[62:65], v[216:219], v[18:21]
	s_barrier
; #define PG8_STAGE(bufoff, gbase, voff) do { _Pragma("unroll") for (int _i = 0; _i < 2; ++_i) \
;         __builtin_amdgcn_global_load_lds((const unsigned*)((const char*)(gbase) + (voff)[_i]), (PG8_LAS unsigned*)(lds + (bufoff) + ldsw + _i * 8192), 16, 0, 0); } while (0)
; #define PG8_LDA(dst, b, h) do { _Pragma("unroll") for (int m = 0; m < 4; ++m) _Pragma("unroll") for (int k = 0; k < 2; ++k) dst[m][k] = *(const PG8_LAS bf16x8*)(lds + PG8_SA(b, h) + aoff + m * 2048 + k * 1024); } while (0)
; #define PG8_LDB(dst, b, h) do { _Pragma("unroll") for (int n = 0; n < 2; ++n) _Pragma("unroll") for (int k = 0; k < 2; ++k) dst[n][k] = *(const PG8_LAS bf16x8*)(lds + PG8_SB(b, h) + boff + n * 2048 + k * 1024); } while (0)
; #define PG8_MMA(ai, bj, At, Bt) do { __builtin_amdgcn_s_setprio(1); _Pragma("unroll") for (int m = 0; m < 4; ++m) _Pragma("unroll") for (int n = 0; n < 2; ++n) _Pragma("unroll") for (int k = 0; k < 2; ++k) \
;         acc[ai][bj][m][n] = __builtin_amdgcn_mfma_f32_16x16x32_bf16(Bt[n][k], At[m][k], acc[ai][bj][m][n], 0, 0, 0); __builtin_amdgcn_s_setprio(0); } while (0)
; #define PG8_WAIT_V(n) asm volatile("s_waitcnt vmcnt(" #n ")" ::: "memory")
; #define PG8_WAIT_L(n) asm volatile("s_waitcnt lgkmcnt(" #n ")" ::: "memory")
; #define PG8_BAR __builtin_amdgcn_s_barrier()
; #define PG8_SCHED __builtin_amdgcn_sched_barrier(0)
; template <class Epi, class Sched, bool ALIGN_EPI = false, bool SP2 = false>
; __device__ __forceinline__ void gemm_phase(PG8_LAS unsigned char* lds, const Gemm g, const Sched& S, const Epi& E) {
;     ...
;             PG8_LDB(B0, 1, 0); PG8_LDB(B1, 1, 1); PG8_SCHED; PG8_LDA(At, 1, 0); PG8_STAGE(PG8_SA(0, 1), a2 + hstep, voffA);
;             PG8_WAIT_V(8); PG8_WAIT_L(0); PG8_BAR; PG8_MMA(0, 0, At, B0); PG8_MMA(0, 1, At, B1); PG8_BAR; PG8_SCHED;
;             PG8_LDA(At, 1, 1); PG8_STAGE(PG8_SB(1, 0), b3, voffB); PG8_STAGE(PG8_SB(1, 1), b3 + hstep, voffB); PG8_STAGE(PG8_SA(1, 0), a3, voffA);
;             PG8_WAIT_V(8); PG8_WAIT_L(0); PG8_BAR; PG8_MMA(1, 0, At, B0); PG8_MMA(1, 1, At, B1); PG8_BAR; PG8_SCHED;
;     ...
;         if constexpr (ALIGN_EPI) { if (wr == 0) PG8_BAR; }
	s_add_i32 s58, 0, 0x18000
	s_add_i32 s59, 0, 0x1c000
	v_add_u32_e32 v54, s58, v1
	v_add_u32_e32 v98, s59, v1
	ds_read_b128 v[26:29], v54
	ds_read_b128 v[30:33], v54 offset:1024
	ds_read_b128 v[50:53], v54 offset:2048
	ds_read_b128 v[54:57], v54 offset:3072
	ds_read_b128 v[58:61], v98
	ds_read_b128 v[62:65], v98 offset:1024
	ds_read_b128 v[170:173], v98 offset:2048
	ds_read_b128 v[174:177], v98 offset:3072
	s_add_u32 s90, s90, 0x100000
	s_addc_u32 s91, s91, 0
	s_mov_b32 m0, s73
	ds_read_b128 v[98:101], v239 offset:32768
	ds_read_b128 v[102:105], v239 offset:33792
	ds_read_b128 v[178:181], v239 offset:34816
	ds_read_b128 v[208:211], v239 offset:35840
	ds_read_b128 v[212:215], v239 offset:36864
	ds_read_b128 v[216:219], v239 offset:37888
	ds_read_b128 v[220:223], v239 offset:38912
	ds_read_b128 v[224:227], v239 offset:39936
	global_load_lds_dwordx4 v184, s[90:91]
	s_mov_b32 m0, s75
	s_nop 0
	global_load_lds_dwordx4 v188, s[90:91]
	s_nop 0
	s_waitcnt vmcnt(8)
	s_waitcnt lgkmcnt(0)
	s_barrier
	s_waitcnt lgkmcnt(0)
	v_mfma_f32_16x16x32_bf16 v[150:153], v[26:29], v[178:181], v[158:161]
	v_mfma_f32_16x16x32_bf16 v[158:161], v[30:33], v[208:211], v[150:153]
	v_mfma_f32_16x16x32_bf16 v[6:9], v[26:29], v[98:101], v[6:9]
	v_mfma_f32_16x16x32_bf16 v[6:9], v[30:33], v[102:105], v[6:9]
	v_mfma_f32_16x16x32_bf16 v[2:5], v[50:53], v[98:101], v[2:5]
	v_mfma_f32_16x16x32_bf16 v[2:5], v[54:57], v[102:105], v[2:5]
	v_mfma_f32_16x16x32_bf16 v[150:153], v[50:53], v[178:181], v[154:157]
	v_mfma_f32_16x16x32_bf16 v[154:157], v[54:57], v[208:211], v[150:153]
	v_mfma_f32_16x16x32_bf16 v[142:145], v[26:29], v[212:215], v[142:145]
	v_mfma_f32_16x16x32_bf16 v[142:145], v[30:33], v[216:219], v[142:145]
	v_mfma_f32_16x16x32_bf16 v[138:141], v[50:53], v[212:215], v[138:141]
	v_mfma_f32_16x16x32_bf16 v[138:141], v[54:57], v[216:219], v[138:141]
	v_mfma_f32_16x16x32_bf16 v[126:129], v[26:29], v[220:223], v[126:129]
	v_mfma_f32_16x16x32_bf16 v[126:129], v[30:33], v[224:227], v[126:129]
	v_mfma_f32_16x16x32_bf16 v[122:125], v[50:53], v[220:223], v[122:125]
	v_mfma_f32_16x16x32_bf16 v[122:125], v[54:57], v[224:227], v[122:125]
	v_mfma_f32_16x16x32_bf16 v[66:69], v[170:173], v[98:101], v[66:69]
	v_mfma_f32_16x16x32_bf16 v[162:165], v[174:177], v[102:105], v[66:69]
	v_mfma_f32_16x16x32_bf16 v[150:153], v[58:61], v[98:101], v[166:169]
	v_mfma_f32_16x16x32_bf16 v[166:169], v[62:65], v[102:105], v[150:153]
	v_mfma_f32_16x16x32_bf16 v[66:69], v[58:61], v[178:181], v[70:73]
	v_mfma_f32_16x16x32_bf16 v[150:153], v[62:65], v[208:211], v[66:69]
	v_mfma_f32_16x16x32_bf16 v[66:69], v[170:173], v[178:181], v[146:149]
	v_mfma_f32_16x16x32_bf16 v[146:149], v[174:177], v[208:211], v[66:69]
	v_mfma_f32_16x16x32_bf16 v[66:69], v[58:61], v[212:215], v[134:137]
	v_mfma_f32_16x16x32_bf16 v[134:137], v[62:65], v[216:219], v[66:69]
	v_mfma_f32_16x16x32_bf16 v[66:69], v[170:173], v[212:215], v[130:133]
	v_mfma_f32_16x16x32_bf16 v[130:133], v[174:177], v[216:219], v[66:69]
	v_mfma_f32_16x16x32_bf16 v[66:69], v[58:61], v[220:223], v[118:121]
	v_mfma_f32_16x16x32_bf16 v[118:121], v[62:65], v[224:227], v[66:69]
	v_mfma_f32_16x16x32_bf16 v[66:69], v[170:173], v[220:223], v[114:117]
	v_mfma_f32_16x16x32_bf16 v[114:117], v[174:177], v[224:227], v[66:69]
	s_barrier
	s_add_i32 s58, s58, s61
	s_add_u32 s100, s88, 0x80
	s_addc_u32 s101, s89, 0
	s_mov_b32 m0, s58
	s_nop 1
	ds_read_b128 v[66:69], v239 offset:49152
	ds_read_b128 v[70:73], v239 offset:50176
	ds_read_b128 v[178:181], v239 offset:51200
	ds_read_b128 v[208:211], v239 offset:52224
	ds_read_b128 v[212:215], v239 offset:53248
	ds_read_b128 v[216:219], v239 offset:54272
	ds_read_b128 v[220:223], v239 offset:55296
	ds_read_b128 v[224:227], v239 offset:56320
	global_load_lds_dwordx4 v186, s[100:101]
	s_add_i32 m0, s58, 0x2000
	s_add_i32 s58, s59, s61
	global_load_lds_dwordx4 v190, s[100:101]
	s_add_u32 s88, s88, 0x100080
	s_addc_u32 s89, s89, 0
	s_add_u32 s100, s90, 0xfff00080
	s_addc_u32 s101, s91, -1
	s_mov_b32 m0, s58
	s_nop 0
	global_load_lds_dwordx4 v186, s[88:89]
	s_add_i32 m0, s58, 0x2000
	s_nop 0
	global_load_lds_dwordx4 v190, s[88:89]
	s_mov_b32 m0, s29
	s_nop 0
	global_load_lds_dwordx4 v184, s[100:101]
	s_mov_b32 m0, s95
	s_nop 0
	global_load_lds_dwordx4 v188, s[100:101]
	s_nop 0
	s_waitcnt vmcnt(8)
	s_waitcnt lgkmcnt(0)
	s_barrier
	s_waitcnt lgkmcnt(0)
	v_mfma_f32_16x16x32_bf16 v[98:101], v[26:29], v[66:69], v[110:113]
	v_mfma_f32_16x16x32_bf16 v[110:113], v[30:33], v[70:73], v[98:101]
	v_mfma_f32_16x16x32_bf16 v[94:97], v[26:29], v[178:181], v[94:97]
	v_mfma_f32_16x16x32_bf16 v[94:97], v[30:33], v[208:211], v[94:97]
	v_mfma_f32_16x16x32_bf16 v[78:81], v[26:29], v[212:215], v[78:81]
	v_mfma_f32_16x16x32_bf16 v[78:81], v[30:33], v[216:219], v[78:81]
	v_mfma_f32_16x16x32_bf16 v[10:13], v[26:29], v[220:223], v[10:13]
	v_mfma_f32_16x16x32_bf16 v[30:33], v[30:33], v[224:227], v[10:13]
	v_mfma_f32_16x16x32_bf16 v[98:101], v[50:53], v[66:69], v[106:109]
	v_mfma_f32_16x16x32_bf16 v[106:109], v[54:57], v[70:73], v[98:101]
	v_mfma_f32_16x16x32_bf16 v[90:93], v[50:53], v[178:181], v[90:93]
	v_mfma_f32_16x16x32_bf16 v[90:93], v[54:57], v[208:211], v[90:93]
	v_mfma_f32_16x16x32_bf16 v[74:77], v[50:53], v[212:215], v[74:77]
	v_mfma_f32_16x16x32_bf16 v[74:77], v[54:57], v[216:219], v[74:77]
	v_mfma_f32_16x16x32_bf16 v[10:13], v[50:53], v[220:223], v[14:17]
	v_mfma_f32_16x16x32_bf16 v[26:29], v[54:57], v[224:227], v[10:13]
	v_mfma_f32_16x16x32_bf16 v[10:13], v[58:61], v[66:69], v[42:45]
	v_mfma_f32_16x16x32_bf16 v[102:105], v[62:65], v[70:73], v[10:13]
	v_mfma_f32_16x16x32_bf16 v[10:13], v[170:173], v[66:69], v[46:49]
	v_mfma_f32_16x16x32_bf16 v[98:101], v[174:177], v[70:73], v[10:13]
	v_mfma_f32_16x16x32_bf16 v[10:13], v[58:61], v[178:181], v[86:89]
	v_mfma_f32_16x16x32_bf16 v[86:89], v[62:65], v[208:211], v[10:13]
	v_mfma_f32_16x16x32_bf16 v[10:13], v[170:173], v[178:181], v[82:85]
	v_mfma_f32_16x16x32_bf16 v[82:85], v[174:177], v[208:211], v[10:13]
	v_mfma_f32_16x16x32_bf16 v[10:13], v[58:61], v[212:215], v[38:41]
	v_mfma_f32_16x16x32_bf16 v[38:41], v[62:65], v[216:219], v[10:13]
	v_mfma_f32_16x16x32_bf16 v[10:13], v[170:173], v[212:215], v[34:37]
	v_mfma_f32_16x16x32_bf16 v[34:37], v[174:177], v[216:219], v[10:13]
	v_mfma_f32_16x16x32_bf16 v[10:13], v[58:61], v[220:223], v[22:25]
	v_mfma_f32_16x16x32_bf16 v[22:25], v[62:65], v[224:227], v[10:13]
	v_mfma_f32_16x16x32_bf16 v[10:13], v[170:173], v[220:223], v[18:21]
	v_mfma_f32_16x16x32_bf16 v[18:21], v[174:177], v[224:227], v[10:13]
	s_barrier
	s_add_i32 s93, s93, 2
	s_add_u32 s86, s86, 0x100
	s_addc_u32 s87, s87, 0
	s_add_u32 s85, s85, 0x100
	s_addc_u32 s92, s92, 0
	s_cmp_gt_u32 s93, 61
	s_cbranch_scc0 .LBB0_2650
	s_and_b64 vcc, exec, s[42:43]
	s_cbranch_vccz .LBB0_2653
	s_barrier

; #define PG8_STAGE(bufoff, gbase, voff) do { _Pragma("unroll") for (int _i = 0; _i < 2; ++_i) \
;         __builtin_amdgcn_global_load_lds((const unsigned*)((const char*)(gbase) + (voff)[_i]), (PG8_LAS unsigned*)(lds + (bufoff) + ldsw + _i * 8192), 16, 0, 0); } while (0)
; #define PG8_LDA(dst, b, h) do { _Pragma("unroll") for (int m = 0; m < 4; ++m) _Pragma("unroll") for (int k = 0; k < 2; ++k) dst[m][k] = *(const PG8_LAS bf16x8*)(lds + PG8_SA(b, h) + aoff + m * 2048 + k * 1024); } while (0)
; #define PG8_LDB(dst, b, h) do { _Pragma("unroll") for (int n = 0; n < 2; ++n) _Pragma("unroll") for (int k = 0; k < 2; ++k) dst[n][k] = *(const PG8_LAS bf16x8*)(lds + PG8_SB(b, h) + boff + n * 2048 + k * 1024); } while (0)
; #define PG8_MMA(ai, bj, At, Bt) do { __builtin_amdgcn_s_setprio(1); _Pragma("unroll") for (int m = 0; m < 4; ++m) _Pragma("unroll") for (int n = 0; n < 2; ++n) _Pragma("unroll") for (int k = 0; k < 2; ++k) \
;         acc[ai][bj][m][n] = __builtin_amdgcn_mfma_f32_16x16x32_bf16(Bt[n][k], At[m][k], acc[ai][bj][m][n], 0, 0, 0); __builtin_amdgcn_s_setprio(0); } while (0)
; #define PG8_WAIT_V(n) asm volatile("s_waitcnt vmcnt(" #n ")" ::: "memory")
; #define PG8_WAIT_L(n) asm volatile("s_waitcnt lgkmcnt(" #n ")" ::: "memory")
; template <class Epi, class Sched, bool ALIGN_EPI = false, bool SP2 = false>
; __device__ __forceinline__ void gemm_phase(PG8_LAS unsigned char* lds, const Gemm g, const Sched& S, const Epi& E) {
;     ...
;             const bool last = (t == ntc - 2);
;             const char* a1 = cA + (size_t)(t + 1) * kstep;
;             const char* a2 = last ? nA : cA + (size_t)(t + 2) * kstep; const char* b2 = last ? nB : cB + (size_t)(t + 2) * kstep;
;             const char* a3 = a2 + kstep; const char* b3 = b2 + kstep;
;             if (last && has_next) S.a_ready(nxt);
;             if constexpr (SP2) {
;             PG8_LDB(B0, 0, 0); PG8_LDB(B1, 0, 1); PG8_SCHED; PG8_LDA(At, 0, 0); PG8_STAGE(PG8_SA(1, 1), a1 + hstep, voffA);
;             PG8_WAIT_V(8); PG8_WAIT_L(0); PG8_BAR; PG8_MMA(0, 0, At, B0); PG8_MMA(0, 1, At, B1); PG8_BAR; PG8_SCHED;
;             PG8_LDA(At, 0, 1); PG8_STAGE(PG8_SB(0, 0), b2, voffB); PG8_STAGE(PG8_SB(0, 1), b2 + hstep, voffB); PG8_STAGE(PG8_SA(0, 0), a2, voffA);
;             PG8_WAIT_V(8); PG8_WAIT_L(0); PG8_BAR; PG8_MMA(1, 0, At, B0); PG8_MMA(1, 1, At, B1); PG8_BAR; PG8_SCHED;
.LBB0_3522:
	ds_read_b128 v[144:147], v177
	ds_read_b128 v[148:151], v177 offset:1024
	ds_read_b128 v[152:155], v177 offset:2048
	ds_read_b128 v[156:159], v177 offset:3072
	ds_read_b128 v[160:163], v178
	ds_read_b128 v[164:167], v178 offset:1024
	ds_read_b128 v[168:171], v178 offset:2048
	ds_read_b128 v[172:175], v178 offset:3072
	s_add_u32 s40, s38, 0x100
	s_addc_u32 s41, s39, 0
	s_cmp_eq_u32 s69, s71
	s_cselect_b32 s45, s35, s41
	s_cselect_b32 s44, s34, s40
	s_cselect_b32 s43, s37, s70
	s_cselect_b32 s42, s36, s31
	s_add_i32 m0, s51, 0xc000
	ds_read_b128 v[180:183], v179
	ds_read_b128 v[184:187], v179 offset:1024
	ds_read_b128 v[188:191], v179 offset:2048
	ds_read_b128 v[192:195], v179 offset:3072
	ds_read_b128 v[196:199], v179 offset:4096
	ds_read_b128 v[200:203], v179 offset:5120
	ds_read_b128 v[204:207], v179 offset:6144
	ds_read_b128 v[208:211], v179 offset:7168
	global_load_lds_dwordx4 v138, s[38:39]
	s_add_i32 m0, s51, 0xe000
	s_nop 0
	global_load_lds_dwordx4 v140, s[38:39]
	s_waitcnt vmcnt(8)
	s_waitcnt lgkmcnt(0)
	s_barrier
	s_waitcnt lgkmcnt(0)
	v_mfma_f32_16x16x32_bf16 v[126:129], v[144:147], v[180:183], v[126:129]
	v_mfma_f32_16x16x32_bf16 v[126:129], v[148:151], v[184:187], v[126:129]
	v_mfma_f32_16x16x32_bf16 v[122:125], v[152:155], v[180:183], v[122:125]
	v_mfma_f32_16x16x32_bf16 v[122:125], v[156:159], v[184:187], v[122:125]
	v_mfma_f32_16x16x32_bf16 v[106:109], v[152:155], v[188:191], v[106:109]
	v_mfma_f32_16x16x32_bf16 v[106:109], v[156:159], v[192:195], v[106:109]
	v_mfma_f32_16x16x32_bf16 v[110:113], v[144:147], v[188:191], v[110:113]
	v_mfma_f32_16x16x32_bf16 v[110:113], v[148:151], v[192:195], v[110:113]
	v_mfma_f32_16x16x32_bf16 v[94:97], v[144:147], v[196:199], v[94:97]
	v_mfma_f32_16x16x32_bf16 v[94:97], v[148:151], v[200:203], v[94:97]
	v_mfma_f32_16x16x32_bf16 v[90:93], v[152:155], v[196:199], v[90:93]
	v_mfma_f32_16x16x32_bf16 v[90:93], v[156:159], v[200:203], v[90:93]
	v_mfma_f32_16x16x32_bf16 v[74:77], v[152:155], v[204:207], v[74:77]
	v_mfma_f32_16x16x32_bf16 v[74:77], v[156:159], v[208:211], v[74:77]
	v_mfma_f32_16x16x32_bf16 v[78:81], v[144:147], v[204:207], v[78:81]
	v_mfma_f32_16x16x32_bf16 v[78:81], v[148:151], v[208:211], v[78:81]
	v_mfma_f32_16x16x32_bf16 v[118:121], v[160:163], v[180:183], v[118:121]
	v_mfma_f32_16x16x32_bf16 v[118:121], v[164:167], v[184:187], v[118:121]
	v_mfma_f32_16x16x32_bf16 v[114:117], v[168:171], v[180:183], v[114:117]
	v_mfma_f32_16x16x32_bf16 v[114:117], v[172:175], v[184:187], v[114:117]
	v_mfma_f32_16x16x32_bf16 v[98:101], v[168:171], v[188:191], v[98:101]
	v_mfma_f32_16x16x32_bf16 v[98:101], v[172:175], v[192:195], v[98:101]
	v_mfma_f32_16x16x32_bf16 v[102:105], v[160:163], v[188:191], v[102:105]
	v_mfma_f32_16x16x32_bf16 v[102:105], v[164:167], v[192:195], v[102:105]
	v_mfma_f32_16x16x32_bf16 v[86:89], v[160:163], v[196:199], v[86:89]
	v_mfma_f32_16x16x32_bf16 v[86:89], v[164:167], v[200:203], v[86:89]
	v_mfma_f32_16x16x32_bf16 v[82:85], v[168:171], v[196:199], v[82:85]
	v_mfma_f32_16x16x32_bf16 v[82:85], v[172:175], v[200:203], v[82:85]
	v_mfma_f32_16x16x32_bf16 v[66:69], v[168:171], v[204:207], v[66:69]
	v_mfma_f32_16x16x32_bf16 v[66:69], v[172:175], v[208:211], v[66:69]
	v_mfma_f32_16x16x32_bf16 v[70:73], v[160:163], v[204:207], v[70:73]
	v_mfma_f32_16x16x32_bf16 v[70:73], v[164:167], v[208:211], v[70:73]
	s_barrier
	s_add_i32 s38, s63, s50
	s_mov_b32 m0, s38
	ds_read_b128 v[180:183], v179 offset:16384
	ds_read_b128 v[184:187], v179 offset:17408
	ds_read_b128 v[188:191], v179 offset:18432
	ds_read_b128 v[192:195], v179 offset:19456
	ds_read_b128 v[196:199], v179 offset:20480
	ds_read_b128 v[200:203], v179 offset:21504
	ds_read_b128 v[204:207], v179 offset:22528
	ds_read_b128 v[208:211], v179 offset:23552
	global_load_lds_dwordx4 v130, s[42:43]
	s_add_i32 m0, s38, 0x2000
	s_add_u32 s38, s42, 0x300000
	s_addc_u32 s39, s43, 0
	s_add_i32 s58, s64, s50
	global_load_lds_dwordx4 v132, s[42:43]
	s_mov_b32 m0, s58
	s_nop 0
	global_load_lds_dwordx4 v130, s[38:39]
	s_add_i32 m0, s58, 0x2000
	s_nop 0
	global_load_lds_dwordx4 v132, s[38:39]
	s_mov_b32 m0, s51
	s_nop 0
	global_load_lds_dwordx4 v130, s[44:45]
	s_mov_b32 m0, s52
	s_nop 0
	global_load_lds_dwordx4 v132, s[44:45]
	s_waitcnt vmcnt(8)
	s_waitcnt lgkmcnt(0)
	s_barrier
	s_waitcnt lgkmcnt(0)
	v_mfma_f32_16x16x32_bf16 v[62:65], v[144:147], v[180:183], v[62:65]
	v_mfma_f32_16x16x32_bf16 v[62:65], v[148:151], v[184:187], v[62:65]
	v_mfma_f32_16x16x32_bf16 v[58:61], v[152:155], v[180:183], v[58:61]
	v_mfma_f32_16x16x32_bf16 v[58:61], v[156:159], v[184:187], v[58:61]
	v_mfma_f32_16x16x32_bf16 v[42:45], v[152:155], v[188:191], v[42:45]
	v_mfma_f32_16x16x32_bf16 v[42:45], v[156:159], v[192:195], v[42:45]
	v_mfma_f32_16x16x32_bf16 v[46:49], v[144:147], v[188:191], v[46:49]
	v_mfma_f32_16x16x32_bf16 v[46:49], v[148:151], v[192:195], v[46:49]
	v_mfma_f32_16x16x32_bf16 v[30:33], v[144:147], v[196:199], v[30:33]
	v_mfma_f32_16x16x32_bf16 v[30:33], v[148:151], v[200:203], v[30:33]
	v_mfma_f32_16x16x32_bf16 v[26:29], v[152:155], v[196:199], v[26:29]
	v_mfma_f32_16x16x32_bf16 v[26:29], v[156:159], v[200:203], v[26:29]
	v_mfma_f32_16x16x32_bf16 v[10:13], v[152:155], v[204:207], v[10:13]
	v_mfma_f32_16x16x32_bf16 v[10:13], v[156:159], v[208:211], v[10:13]
	v_mfma_f32_16x16x32_bf16 v[14:17], v[144:147], v[204:207], v[14:17]
	v_mfma_f32_16x16x32_bf16 v[14:17], v[148:151], v[208:211], v[14:17]
	v_mfma_f32_16x16x32_bf16 v[54:57], v[160:163], v[180:183], v[54:57]
	v_mfma_f32_16x16x32_bf16 v[54:57], v[164:167], v[184:187], v[54:57]
	v_mfma_f32_16x16x32_bf16 v[50:53], v[168:171], v[180:183], v[50:53]
	v_mfma_f32_16x16x32_bf16 v[50:53], v[172:175], v[184:187], v[50:53]
	v_mfma_f32_16x16x32_bf16 v[34:37], v[168:171], v[188:191], v[34:37]
	v_mfma_f32_16x16x32_bf16 v[34:37], v[172:175], v[192:195], v[34:37]
	v_mfma_f32_16x16x32_bf16 v[38:41], v[160:163], v[188:191], v[38:41]
	v_mfma_f32_16x16x32_bf16 v[38:41], v[164:167], v[192:195], v[38:41]
	v_mfma_f32_16x16x32_bf16 v[22:25], v[160:163], v[196:199], v[22:25]
	v_mfma_f32_16x16x32_bf16 v[22:25], v[164:167], v[200:203], v[22:25]
	v_mfma_f32_16x16x32_bf16 v[18:21], v[168:171], v[196:199], v[18:21]
	v_mfma_f32_16x16x32_bf16 v[18:21], v[172:175], v[200:203], v[18:21]
	v_mfma_f32_16x16x32_bf16 v[2:5], v[168:171], v[204:207], v[2:5]
	v_mfma_f32_16x16x32_bf16 v[2:5], v[172:175], v[208:211], v[2:5]
	v_mfma_f32_16x16x32_bf16 v[6:9], v[160:163], v[204:207], v[6:9]
	v_mfma_f32_16x16x32_bf16 v[6:9], v[164:167], v[208:211], v[6:9]
	s_barrier
; #define PG8_STAGE(bufoff, gbase, voff) do { _Pragma("unroll") for (int _i = 0; _i < 2; ++_i) \
;         __builtin_amdgcn_global_load_lds((const unsigned*)((const char*)(gbase) + (voff)[_i]), (PG8_LAS unsigned*)(lds + (bufoff) + ldsw + _i * 8192), 16, 0, 0); } while (0)
; #define PG8_LDA(dst, b, h) do { _Pragma("unroll") for (int m = 0; m < 4; ++m) _Pragma("unroll") for (int k = 0; k < 2; ++k) dst[m][k] = *(const PG8_LAS bf16x8*)(lds + PG8_SA(b, h) + aoff + m * 2048 + k * 1024); } while (0)
; #define PG8_LDB(dst, b, h) do { _Pragma("unroll") for (int n = 0; n < 2; ++n) _Pragma("unroll") for (int k = 0; k < 2; ++k) dst[n][k] = *(const PG8_LAS bf16x8*)(lds + PG8_SB(b, h) + boff + n * 2048 + k * 1024); } while (0)
; #define PG8_MMA(ai, bj, At, Bt) do { __builtin_amdgcn_s_setprio(1); _Pragma("unroll") for (int m = 0; m < 4; ++m) _Pragma("unroll") for (int n = 0; n < 2; ++n) _Pragma("unroll") for (int k = 0; k < 2; ++k) \
;         acc[ai][bj][m][n] = __builtin_amdgcn_mfma_f32_16x16x32_bf16(Bt[n][k], At[m][k], acc[ai][bj][m][n], 0, 0, 0); __builtin_amdgcn_s_setprio(0); } while (0)
; #define PG8_WAIT_V(n) asm volatile("s_waitcnt vmcnt(" #n ")" ::: "memory")
; #define PG8_WAIT_L(n) asm volatile("s_waitcnt lgkmcnt(" #n ")" ::: "memory")
; #define PG8_BAR __builtin_amdgcn_s_barrier()
; #define PG8_SCHED __builtin_amdgcn_sched_barrier(0)
;     __device__ __forceinline__ void operator()(const f32x4 (&acc)[2][2][4][2], const Unit& u, int wr, int wc, int fr, int fq) const {
;     ...
;         if (u.ntu != 192) {
; template <class Epi, class Sched, bool ALIGN_EPI = false, bool SP2 = false>
; __device__ __forceinline__ void gemm_phase(PG8_LAS unsigned char* lds, const Gemm g, const Sched& S, const Epi& E) {
;     ...
;             PG8_LDB(B0, 1, 0); PG8_LDB(B1, 1, 1); PG8_SCHED; PG8_LDA(At, 1, 0); PG8_STAGE(PG8_SA(0, 1), a2 + hstep, voffA);
;             PG8_WAIT_V(8); PG8_WAIT_L(0); PG8_BAR; PG8_MMA(0, 0, At, B0); PG8_MMA(0, 1, At, B1); PG8_BAR; PG8_SCHED;
;             PG8_LDA(At, 1, 1); PG8_STAGE(PG8_SB(1, 0), b3, voffB); PG8_STAGE(PG8_SB(1, 1), b3 + hstep, voffB); PG8_STAGE(PG8_SA(1, 0), a3, voffA);
;             PG8_WAIT_V(8); PG8_WAIT_L(0); PG8_BAR; PG8_MMA(1, 0, At, B0); PG8_MMA(1, 1, At, B1); PG8_BAR; PG8_SCHED;
	s_add_i32 s58, 0, 0x18000
	v_add_u32_e32 v134, s58, v1
	s_add_i32 s59, 0, 0x1c000
	ds_read_b128 v[144:147], v134
	ds_read_b128 v[148:151], v134 offset:1024
	ds_read_b128 v[152:155], v134 offset:2048
	ds_read_b128 v[156:159], v134 offset:3072
	v_add_u32_e32 v134, s59, v1
	ds_read_b128 v[160:163], v134
	ds_read_b128 v[164:167], v134 offset:1024
	ds_read_b128 v[168:171], v134 offset:2048
	ds_read_b128 v[172:175], v134 offset:3072
	s_add_u32 s38, s44, 0x300000
	s_addc_u32 s39, s45, 0
	s_mov_b32 m0, s53
	ds_read_b128 v[180:183], v179 offset:32768
	ds_read_b128 v[184:187], v179 offset:33792
	ds_read_b128 v[188:191], v179 offset:34816
	ds_read_b128 v[192:195], v179 offset:35840
	ds_read_b128 v[196:199], v179 offset:36864
	ds_read_b128 v[200:203], v179 offset:37888
	ds_read_b128 v[204:207], v179 offset:38912
	ds_read_b128 v[208:211], v179 offset:39936
	global_load_lds_dwordx4 v130, s[38:39]
	s_mov_b32 m0, s54
	s_nop 0
	global_load_lds_dwordx4 v132, s[38:39]
	s_nop 0
	s_waitcnt vmcnt(8)
	s_waitcnt lgkmcnt(0)
	s_barrier
	s_waitcnt lgkmcnt(0)
	v_mfma_f32_16x16x32_bf16 v[126:129], v[144:147], v[180:183], v[126:129]
	v_mfma_f32_16x16x32_bf16 v[126:129], v[148:151], v[184:187], v[126:129]
	v_mfma_f32_16x16x32_bf16 v[122:125], v[152:155], v[180:183], v[122:125]
	v_mfma_f32_16x16x32_bf16 v[122:125], v[156:159], v[184:187], v[122:125]
	v_mfma_f32_16x16x32_bf16 v[106:109], v[152:155], v[188:191], v[106:109]
	v_mfma_f32_16x16x32_bf16 v[106:109], v[156:159], v[192:195], v[106:109]
	v_mfma_f32_16x16x32_bf16 v[110:113], v[144:147], v[188:191], v[110:113]
	v_mfma_f32_16x16x32_bf16 v[110:113], v[148:151], v[192:195], v[110:113]
	v_mfma_f32_16x16x32_bf16 v[94:97], v[144:147], v[196:199], v[94:97]
	v_mfma_f32_16x16x32_bf16 v[94:97], v[148:151], v[200:203], v[94:97]
	v_mfma_f32_16x16x32_bf16 v[90:93], v[152:155], v[196:199], v[90:93]
	v_mfma_f32_16x16x32_bf16 v[90:93], v[156:159], v[200:203], v[90:93]
	v_mfma_f32_16x16x32_bf16 v[74:77], v[152:155], v[204:207], v[74:77]
	v_mfma_f32_16x16x32_bf16 v[74:77], v[156:159], v[208:211], v[74:77]
	v_mfma_f32_16x16x32_bf16 v[78:81], v[144:147], v[204:207], v[78:81]
	v_mfma_f32_16x16x32_bf16 v[78:81], v[148:151], v[208:211], v[78:81]
	v_mfma_f32_16x16x32_bf16 v[118:121], v[160:163], v[180:183], v[118:121]
	v_mfma_f32_16x16x32_bf16 v[118:121], v[164:167], v[184:187], v[118:121]
	v_mfma_f32_16x16x32_bf16 v[114:117], v[168:171], v[180:183], v[114:117]
	v_mfma_f32_16x16x32_bf16 v[114:117], v[172:175], v[184:187], v[114:117]
	v_mfma_f32_16x16x32_bf16 v[98:101], v[168:171], v[188:191], v[98:101]
	v_mfma_f32_16x16x32_bf16 v[98:101], v[172:175], v[192:195], v[98:101]
	v_mfma_f32_16x16x32_bf16 v[102:105], v[160:163], v[188:191], v[102:105]
	v_mfma_f32_16x16x32_bf16 v[102:105], v[164:167], v[192:195], v[102:105]
	v_mfma_f32_16x16x32_bf16 v[86:89], v[160:163], v[196:199], v[86:89]
	v_mfma_f32_16x16x32_bf16 v[86:89], v[164:167], v[200:203], v[86:89]
	v_mfma_f32_16x16x32_bf16 v[82:85], v[168:171], v[196:199], v[82:85]
	v_mfma_f32_16x16x32_bf16 v[82:85], v[172:175], v[200:203], v[82:85]
	v_mfma_f32_16x16x32_bf16 v[66:69], v[168:171], v[204:207], v[66:69]
	v_mfma_f32_16x16x32_bf16 v[66:69], v[172:175], v[208:211], v[66:69]
	v_mfma_f32_16x16x32_bf16 v[70:73], v[160:163], v[204:207], v[70:73]
	v_mfma_f32_16x16x32_bf16 v[70:73], v[164:167], v[208:211], v[70:73]
	s_barrier
	s_add_i32 s38, s58, s50
	s_add_u32 s98, s42, 0x80
	s_addc_u32 s99, s43, 0
	s_add_u32 s100, s44, 0x80
	s_addc_u32 s101, s45, 0
	s_mov_b32 m0, s38
	ds_read_b128 v[180:183], v179 offset:49152
	ds_read_b128 v[184:187], v179 offset:50176
	ds_read_b128 v[188:191], v179 offset:51200
	ds_read_b128 v[192:195], v179 offset:52224
	ds_read_b128 v[196:199], v179 offset:53248
	ds_read_b128 v[200:203], v179 offset:54272
	ds_read_b128 v[204:207], v179 offset:55296
	ds_read_b128 v[208:211], v179 offset:56320
	global_load_lds_dwordx4 v130, s[98:99]
	s_add_i32 m0, s38, 0x2000
	s_add_u32 s38, s42, 0x300080
	s_addc_u32 s39, s43, 0
	s_add_i32 s42, s59, s50
	global_load_lds_dwordx4 v132, s[98:99]
	s_mov_b32 m0, s42
	s_nop 0
	global_load_lds_dwordx4 v130, s[38:39]
	s_add_i32 m0, s42, 0x2000
	s_nop 0
	global_load_lds_dwordx4 v132, s[38:39]
	s_mov_b32 m0, s57
	s_nop 0
	global_load_lds_dwordx4 v130, s[100:101]
	s_mov_b32 m0, s60
	s_nop 0
	global_load_lds_dwordx4 v132, s[100:101]
	s_waitcnt vmcnt(8)
	s_waitcnt lgkmcnt(0)
	s_barrier
	s_waitcnt lgkmcnt(0)
	v_mfma_f32_16x16x32_bf16 v[62:65], v[144:147], v[180:183], v[62:65]
	v_mfma_f32_16x16x32_bf16 v[62:65], v[148:151], v[184:187], v[62:65]
	v_mfma_f32_16x16x32_bf16 v[58:61], v[152:155], v[180:183], v[58:61]
	v_mfma_f32_16x16x32_bf16 v[58:61], v[156:159], v[184:187], v[58:61]
	v_mfma_f32_16x16x32_bf16 v[42:45], v[152:155], v[188:191], v[42:45]
	v_mfma_f32_16x16x32_bf16 v[42:45], v[156:159], v[192:195], v[42:45]
	v_mfma_f32_16x16x32_bf16 v[46:49], v[144:147], v[188:191], v[46:49]
	v_mfma_f32_16x16x32_bf16 v[46:49], v[148:151], v[192:195], v[46:49]
	v_mfma_f32_16x16x32_bf16 v[30:33], v[144:147], v[196:199], v[30:33]
	v_mfma_f32_16x16x32_bf16 v[30:33], v[148:151], v[200:203], v[30:33]
	v_mfma_f32_16x16x32_bf16 v[26:29], v[152:155], v[196:199], v[26:29]
	v_mfma_f32_16x16x32_bf16 v[26:29], v[156:159], v[200:203], v[26:29]
	v_mfma_f32_16x16x32_bf16 v[10:13], v[152:155], v[204:207], v[10:13]
	v_mfma_f32_16x16x32_bf16 v[10:13], v[156:159], v[208:211], v[10:13]
	v_mfma_f32_16x16x32_bf16 v[14:17], v[144:147], v[204:207], v[14:17]
	v_mfma_f32_16x16x32_bf16 v[14:17], v[148:151], v[208:211], v[14:17]
	v_mfma_f32_16x16x32_bf16 v[54:57], v[160:163], v[180:183], v[54:57]
	v_mfma_f32_16x16x32_bf16 v[54:57], v[164:167], v[184:187], v[54:57]
	v_mfma_f32_16x16x32_bf16 v[50:53], v[168:171], v[180:183], v[50:53]
	v_mfma_f32_16x16x32_bf16 v[50:53], v[172:175], v[184:187], v[50:53]
	v_mfma_f32_16x16x32_bf16 v[34:37], v[168:171], v[188:191], v[34:37]
	v_mfma_f32_16x16x32_bf16 v[34:37], v[172:175], v[192:195], v[34:37]
	v_mfma_f32_16x16x32_bf16 v[38:41], v[160:163], v[188:191], v[38:41]
	v_mfma_f32_16x16x32_bf16 v[38:41], v[164:167], v[192:195], v[38:41]
	v_mfma_f32_16x16x32_bf16 v[22:25], v[160:163], v[196:199], v[22:25]
	v_mfma_f32_16x16x32_bf16 v[22:25], v[164:167], v[200:203], v[22:25]
	v_mfma_f32_16x16x32_bf16 v[18:21], v[168:171], v[196:199], v[18:21]
	v_mfma_f32_16x16x32_bf16 v[18:21], v[172:175], v[200:203], v[18:21]
	v_mfma_f32_16x16x32_bf16 v[2:5], v[168:171], v[204:207], v[2:5]
	v_mfma_f32_16x16x32_bf16 v[2:5], v[172:175], v[208:211], v[2:5]
	v_mfma_f32_16x16x32_bf16 v[6:9], v[160:163], v[204:207], v[6:9]
	v_mfma_f32_16x16x32_bf16 v[6:9], v[164:167], v[208:211], v[6:9]
	s_barrier
	s_add_i32 s42, s71, 2
	s_add_u32 s31, s31, 0x100
	s_addc_u32 s70, s70, 0
	s_cmp_ge_i32 s71, s69
	s_mov_b64 s[38:39], s[40:41]
	s_mov_b32 s71, s42
	s_cbranch_scc0 .LBB0_3522
	s_and_b64 vcc, exec, s[20:21]
	s_cbranch_vccz .LBB0_3543
	s_barrier
	v_lshl_or_b32 v144, s5, 8, v176
	s_cmpk_eq_i32 s69, 0xc0
	s_mov_b64 s[38:39], -1
	s_cbranch_scc0 .LBB0_3544
